# pk4 + 64-byte instruction-fetch alignment of 61 hot loop heads
# baseline (speedup 1.0000x reference)
.LBB0_5:
	s_or_b64 exec, exec, s[4:5]
	s_ashr_i32 s4, s9, 6
	s_lshl_b32 s5, s8, 3
	s_add_i32 s18, s4, s5
	s_cmpk_gt_i32 s18, 0x3fff
	v_mbcnt_lo_u32_b32 v72, -1, 0
	s_cbranch_scc1 .LBB0_46
	v_and_b32_e32 v2, 63, v1
	v_mbcnt_hi_u32_b32 v3, -1, v72
	v_mov_b32_e32 v5, 0
	v_lshlrev_b32_e32 v4, 2, v2
	v_and_b32_e32 v1, 64, v3
	v_lshl_add_u64 v[66:67], s[2:3], 0, v[4:5]
	v_add_u32_e32 v4, 64, v1
	v_xor_b32_e32 v1, 32, v3
	v_cmp_lt_i32_e32 vcc, v1, v4
	v_xor_b32_e32 v6, 16, v3
	s_load_dwordx2 s[0:1], s[0:1], 0x0
	v_cndmask_b32_e32 v1, v3, v1, vcc
	v_cmp_lt_i32_e32 vcc, v6, v4
	s_lshl_b32 s25, s27, 3
	v_cmp_gt_u32_e64 s[4:5], 16, v2
	v_cndmask_b32_e32 v6, v3, v6, vcc
	v_lshlrev_b32_e32 v73, 2, v6
	v_xor_b32_e32 v6, 8, v3
	v_cmp_lt_i32_e32 vcc, v6, v4
	v_cmp_eq_u32_e64 s[6:7], 0, v2
	v_lshlrev_b32_e32 v1, 2, v1
	v_cndmask_b32_e32 v6, v3, v6, vcc
	v_lshlrev_b32_e32 v74, 2, v6
	v_xor_b32_e32 v6, 4, v3
	v_cmp_lt_i32_e32 vcc, v6, v4
	s_lshl_b32 s26, s27, 4
	s_mul_i32 s27, s27, 24
	v_cndmask_b32_e32 v6, v3, v6, vcc
	v_lshlrev_b32_e32 v75, 2, v6
	v_xor_b32_e32 v6, 2, v3
	v_cmp_lt_i32_e32 vcc, v6, v4
	v_lshlrev_b32_e32 v78, 4, v2
	s_nop 0
	v_cndmask_b32_e32 v6, v3, v6, vcc
	v_lshlrev_b32_e32 v76, 2, v6
	v_xor_b32_e32 v6, 1, v3
	v_cmp_lt_i32_e32 vcc, v6, v4
	v_lshlrev_b32_e32 v4, 4, v2
	s_waitcnt lgkmcnt(0)
	v_lshl_add_u64 v[68:69], s[0:1], 0, v[4:5]
	v_lshlrev_b32_e32 v4, 3, v2
	v_cndmask_b32_e32 v3, v3, v6, vcc
	v_lshl_add_u64 v[4:5], s[2:3], 0, v[4:5]
	s_mov_b64 s[2:3], 0xbe00000
	v_lshlrev_b32_e32 v77, 2, v3
	v_lshl_add_u64 v[70:71], v[4:5], 0, s[2:3]
	s_branch .LBB0_9
	.p2align 6
.LBB0_7:
	s_or_b64 exec, exec, s[8:9]
	.p2align 6

.LBB0_49:
	s_mov_b32 s33, 1
	s_cmp_lt_i32 s33, 1
	s_cbranch_scc1 .LBB0_330
	v_readlane_b32 s6, v254, 17
	v_readlane_b32 s7, v254, 18
	s_mov_b32 s8, s6
	s_mul_i32 s80, s6, 0x4c8000
	s_lshl_b32 s0, s6, 10
	s_mov_b32 s1, s81
	s_mov_b32 s7, s81
	v_writelane_b32 v254, s8, 17
	s_lshl_b32 s56, s6, 1
	s_lshl_b32 s2, s6, 19
	s_mov_b32 s3, s81
	s_lshl_b32 s4, s6, 20
	s_mov_b32 s5, s81
	s_lshl_b32 s12, s6, 22
	s_mov_b32 s13, s81
	s_lshl_b64 s[14:15], s[6:7], 22
	v_writelane_b32 v254, s9, 18
	s_lshl_b64 s[16:17], s[6:7], 14
	s_mov_b32 s57, 0
	s_lshl_b64 s[18:19], s[80:81], 2
	s_lshl_b64 s[20:21], s[0:1], 2
	s_branch .LBB0_52
	.p2align 6

.LBB0_65:
	s_andn2_b64 vcc, exec, s[8:9]
	s_mov_b32 s26, 0
	s_cbranch_vccnz .LBB0_67
	.p2align 6
.LBB0_66:
	s_load_dwordx2 s[8:9], s[0:1], 0x50
	s_lshl_b64 s[10:11], s[2:3], 2
	s_mov_b32 s27, 8
	s_movk_i32 s30, 0x3a0
	s_movk_i32 s61, 0x400
	s_waitcnt lgkmcnt(0)
	s_add_u32 s10, s8, s10
	s_addc_u32 s11, s9, s11
	s_add_u32 s24, s22, 0xd00000
	s_addc_u32 s25, s23, 0
	s_movk_i32 s26, 0x200
	s_movk_i32 s62, 0x400
	.p2align 6

.LBB0_131:
	s_or_b64 exec, exec, s[8:9]
	s_and_b64 vcc, exec, s[34:35]
	s_cbranch_vccz .LBB0_328
	s_ashr_i32 s31, s30, 31
	v_lshl_add_u64 v[26:27], s[30:31], 0, v[66:67]
	v_lshl_add_u64 v[26:27], v[26:27], 2, s[28:29]
	global_load_dword v110, v[26:27], off offset:224
	s_cbranch_execnz .LBB0_134
	.p2align 6

.LBB0_134:
	v_and_b32_e32 v0, 63, v69
	v_lshlrev_b32_e32 v84, 4, v0
	s_waitcnt lgkmcnt(0)
	s_add_u32 s28, s22, 0x300000
	v_lshlrev_b32_e32 v0, 2, v0
	s_movk_i32 s6, 0x410
	v_ashrrev_i32_e32 v85, 3, v69
	s_addc_u32 s29, s23, 0
	v_sub_u32_e32 v89, 0x200, v0
	v_ashrrev_i32_e32 v0, 5, v69
	v_mul_lo_u32 v26, v66, s6
	v_and_b32_e32 v33, 7, v69
	v_mov_b32_e32 v38, s59
	s_movk_i32 s6, 0x2080
	s_add_u32 s65, s22, 0x2300000
	v_bitop3_b32 v0, v0, v69, 7 bitop3:0x78
	v_lshlrev_b32_e32 v41, 2, v85
	v_mad_u32_u24 v38, v33, s6, v38
	v_lshlrev_b32_e32 v68, 3, v33
	v_add_u32_e32 v33, 0x200, v69
	s_addc_u32 s66, s23, 0
	v_lshlrev_b32_e32 v0, 4, v0
	v_and_b32_e32 v41, 12, v41
	v_ashrrev_i32_e32 v86, 3, v33
	s_add_u32 s67, s22, 0x2100000
	v_add3_u32 v91, v38, v0, v41
	v_ashrrev_i32_e32 v0, 5, v33
	s_addc_u32 s68, s23, 0
	v_bitop3_b32 v0, v0, v69, 7 bitop3:0x78
	v_lshlrev_b32_e32 v33, 2, v86
	v_add_u32_e32 v39, 0x400, v69
	s_add_u32 s30, s22, 0xd00000
	v_lshlrev_b32_e32 v0, 4, v0
	v_and_b32_e32 v33, 12, v33
	v_ashrrev_i32_e32 v87, 3, v39
	s_addc_u32 s31, s23, 0
	v_add3_u32 v92, v38, v0, v33
	v_ashrrev_i32_e32 v0, 5, v39
	s_add_u32 s34, s22, 0xf00000
	v_bitop3_b32 v0, v0, v69, 7 bitop3:0x78
	v_lshlrev_b32_e32 v33, 2, v87
	v_add_u32_e32 v40, 0x600, v69
	s_addc_u32 s35, s23, 0
	v_lshlrev_b32_e32 v0, 4, v0
	v_and_b32_e32 v33, 12, v33
	v_ashrrev_i32_e32 v88, 3, v40
	s_add_u32 s36, s22, 0x1900000
	v_add3_u32 v93, v38, v0, v33
	v_ashrrev_i32_e32 v0, 5, v40
	s_addc_u32 s37, s23, 0
	v_bitop3_b32 v0, v0, v69, 7 bitop3:0x78
	v_lshlrev_b32_e32 v33, 2, v88
	v_add_u32_e32 v83, s59, v26
	v_xor_b32_e32 v26, 16, v84
	v_xor_b32_e32 v27, 32, v84
	v_xor_b32_e32 v28, 48, v84
	v_xor_b32_e32 v29, 64, v84
	v_xor_b32_e32 v30, 0x50, v84
	v_xor_b32_e32 v31, 0x60, v84
	v_xor_b32_e32 v32, 0x70, v84
	s_add_u32 s38, s22, 0x1100000
	v_lshlrev_b32_e32 v0, 4, v0
	v_and_b32_e32 v33, 12, v33
	s_addc_u32 s39, s23, 0
	v_add3_u32 v94, v38, v0, v33
	v_add_u32_e32 v95, v83, v26
	v_add_u32_e32 v96, v83, v27
	v_add_u32_e32 v97, v83, v28
	v_add_u32_e32 v98, v83, v29
	v_add_u32_e32 v99, v83, v30
	v_add_u32_e32 v100, v83, v31
	v_add_u32_e32 v101, v83, v32
	s_mov_b32 s69, s60
	s_branch .LBB0_137
	.p2align 6
.LBB0_135:
	s_or_b64 exec, exec, s[6:7]
	s_barrier
	.p2align 6

.LBB0_149:
	s_mov_b64 s[6:7], 0
	s_andn2_b64 vcc, exec, s[10:11]
	s_mov_b64 s[44:45], 0
	s_cbranch_vccnz .LBB0_151
	.p2align 6
.LBB0_150:
	s_load_dwordx2 s[10:11], s[0:1], 0x50
	s_lshl_b64 s[40:41], s[2:3], 2
	s_mov_b32 s53, 8
	s_movk_i32 s52, 0x3a0
	s_movk_i32 s71, 0x400
	s_waitcnt lgkmcnt(0)
	s_add_u32 s48, s10, s40
	s_addc_u32 s49, s11, s41
	s_mov_b64 s[40:41], 0x400
	s_mov_b64 s[44:45], 0x200
	s_mov_b64 s[42:43], s[30:31]
	.p2align 6

.LBB0_239:
	s_load_dwordx2 s[8:9], s[0:1], 0x50
	s_lshl_b64 s[24:25], s[2:3], 2
	s_mov_b32 s53, 8
	s_movk_i32 s52, 0x3a0
	s_movk_i32 s61, 0x400
	s_waitcnt lgkmcnt(0)
	s_add_u32 s48, s8, s24
	s_addc_u32 s49, s9, s25
	s_movk_i32 s26, 0x200
	s_movk_i32 s62, 0x400
	s_mov_b64 s[24:25], s[30:31]
	.p2align 6

.LBB0_391:
	s_add_u32 s4, s0, 0x2400000
	s_addc_u32 s5, s1, 0
	s_lshl_b32 s9, s14, 5
	s_and_b32 s9, s9, 0x60
	s_add_i32 m0, s42, 0x18000
	v_lshl_add_u64 v[8:9], v[8:9], 0, s[88:89]
	s_lshl_b32 s46, s7, 6
	s_lshl_b32 s7, s7, 13
	s_lshl_b32 s13, s9, 7
	s_waitcnt vmcnt(2)
	s_barrier
	global_load_lds_dwordx4 v[8:9], off
	v_lshl_add_u64 v[6:7], v[6:7], 0, s[88:89]
	s_add_i32 m0, s42, 0x1a000
	s_add_i32 s47, s42, 0x8000
	s_add_i32 s48, s42, 0xa000
	global_load_lds_dwordx4 v[6:7], off
	v_lshl_add_u64 v[2:3], v[2:3], 0, s[88:89]
	s_mov_b32 m0, s47
	s_add_u32 s14, s24, 0x40080
	global_load_lds_dwordx4 v[2:3], off
	v_lshl_add_u64 v[2:3], v[4:5], 0, s[88:89]
	s_mov_b32 m0, s48
	s_addc_u32 s15, s25, 0
	global_load_lds_dwordx4 v[2:3], off
	s_add_i32 m0, s42, 0x1c000
	v_lshl_add_u64 v[2:3], s[14:15], 0, v[132:133]
	global_load_lds_dwordx4 v[2:3], off
	v_lshl_add_u64 v[2:3], s[14:15], 0, v[136:137]
	s_add_i32 m0, s42, 0x1e000
	v_and_b32_e32 v141, 15, v0
	global_load_lds_dwordx4 v[2:3], off
	v_lshrrev_b32_e32 v2, 1, v0
	v_and_b32_e32 v2, 24, v2
	v_lshlrev_b32_e32 v3, 1, v2
	v_lshlrev_b32_e32 v4, 2, v0
	v_lshl_or_b32 v3, v141, 6, v3
	v_and_b32_e32 v4, 32, v4
	v_or_b32_e32 v138, s9, v2
	v_bitop3_b32 v145, s9, 56, v2 bitop3:0xc8
	v_bfe_u32 v2, v0, 2, 2
	v_bitop3_b32 v5, v3, s7, v4 bitop3:0xde
	v_bitop3_b32 v143, v3, s13, v4 bitop3:0xde
	v_and_b32_e32 v3, 12, v0
	v_cmp_ne_u32_e32 vcc, 2, v2
	v_or_b32_e32 v147, 16, v141
	v_or_b32_e32 v158, 32, v141
	v_cndmask_b32_e32 v3, 4, v3, vcc
	v_cmp_ne_u32_e32 vcc, 1, v2
	v_or_b32_e32 v159, 48, v141
	s_waitcnt vmcnt(6)
	s_cmpk_lt_u32 s6, 0x100
	v_cndmask_b32_e32 v2, 8, v3, vcc
	v_and_or_b32 v140, v0, 3, v2
	v_lshlrev_b32_e32 v0, 14, v10
	v_and_b32_e32 v0, 0xffff8000, v0
	v_and_or_b32 v142, v147, 19, v2
	v_and_or_b32 v144, v158, 35, v2
	v_and_or_b32 v146, v159, 51, v2
	v_lshl_add_u32 v0, v11, 11, v0
	v_and_b32_e32 v2, 1, v10
	v_lshl_or_b32 v0, v2, 6, v0
	v_lshl_add_u32 v148, v12, 1, v0
	v_lshlrev_b32_e32 v0, 14, v13
	v_and_b32_e32 v0, 0xffff8000, v0
	v_lshl_add_u32 v0, v14, 11, v0
	v_and_b32_e32 v2, 1, v13
	v_lshl_or_b32 v0, v2, 6, v0
	s_cselect_b64 s[14:15], -1, 0
	s_ashr_i32 s49, s36, 31
	s_ashr_i32 s50, s33, 31
	v_mov_b32_e32 v139, v1
	v_mov_b32_e32 v149, v1
	v_lshl_add_u32 v150, v15, 1, v0
	v_mov_b32_e32 v151, v1
	s_mov_b32 s51, 0
	v_add_u32_e32 v161, 0, v5
	s_barrier
	s_branch .LBB0_394
	.p2align 6
.LBB0_392:
	s_mov_b64 s[6:7], 0
	.p2align 6

.LBB0_396:
	s_ashr_i32 s19, s18, 31
	s_lshl_b64 s[20:21], s[18:19], 19
	s_add_u32 s20, s37, s20
	s_addc_u32 s21, s38, s21
	s_and_b64 s[22:23], s[6:7], exec
	s_cselect_b32 s9, s21, s11
	s_cselect_b32 s13, s20, s10
	s_ashr_i32 s17, s16, 31
	s_lshl_b64 s[22:23], s[16:17], 19
	s_add_u32 s22, s39, s22
	s_addc_u32 s23, s40, s23
	s_and_b64 s[26:27], s[6:7], exec
	s_cselect_b32 s17, s23, s25
	s_cselect_b32 s19, s22, s24
	s_add_u32 s10, s10, 0x40080
	s_addc_u32 s11, s11, 0
	s_add_u32 s28, s24, 0x100
	v_mov_b32_e32 v2, 0
	s_addc_u32 s29, s25, 0
	s_mov_b32 s30, -2
	v_mov_b32_e32 v3, v2
	v_mov_b32_e32 v4, v2
	v_mov_b32_e32 v5, v2
	v_mov_b32_e32 v6, v2
	v_mov_b32_e32 v7, v2
	v_mov_b32_e32 v8, v2
	v_mov_b32_e32 v9, v2
	v_mov_b32_e32 v18, v2
	v_mov_b32_e32 v19, v2
	v_mov_b32_e32 v20, v2
	v_mov_b32_e32 v21, v2
	v_mov_b32_e32 v22, v2
	v_mov_b32_e32 v23, v2
	v_mov_b32_e32 v24, v2
	v_mov_b32_e32 v25, v2
	v_mov_b32_e32 v34, v2
	v_mov_b32_e32 v35, v2
	v_mov_b32_e32 v36, v2
	v_mov_b32_e32 v37, v2
	v_mov_b32_e32 v38, v2
	v_mov_b32_e32 v39, v2
	v_mov_b32_e32 v40, v2
	v_mov_b32_e32 v41, v2
	v_mov_b32_e32 v50, v2
	v_mov_b32_e32 v51, v2
	v_mov_b32_e32 v52, v2
	v_mov_b32_e32 v53, v2
	v_mov_b32_e32 v54, v2
	v_mov_b32_e32 v55, v2
	v_mov_b32_e32 v56, v2
	v_mov_b32_e32 v57, v2
	v_mov_b32_e32 v10, v2
	v_mov_b32_e32 v11, v2
	v_mov_b32_e32 v12, v2
	v_mov_b32_e32 v13, v2
	v_mov_b32_e32 v14, v2
	v_mov_b32_e32 v15, v2
	v_mov_b32_e32 v16, v2
	v_mov_b32_e32 v17, v2
	v_mov_b32_e32 v26, v2
	v_mov_b32_e32 v27, v2
	v_mov_b32_e32 v28, v2
	v_mov_b32_e32 v29, v2
	v_mov_b32_e32 v30, v2
	v_mov_b32_e32 v31, v2
	v_mov_b32_e32 v32, v2
	v_mov_b32_e32 v33, v2
	v_mov_b32_e32 v42, v2
	v_mov_b32_e32 v43, v2
	v_mov_b32_e32 v44, v2
	v_mov_b32_e32 v45, v2
	v_mov_b32_e32 v46, v2
	v_mov_b32_e32 v47, v2
	v_mov_b32_e32 v48, v2
	v_mov_b32_e32 v49, v2
	v_mov_b32_e32 v58, v2
	v_mov_b32_e32 v59, v2
	v_mov_b32_e32 v60, v2
	v_mov_b32_e32 v61, v2
	v_mov_b32_e32 v62, v2
	v_mov_b32_e32 v63, v2
	v_mov_b32_e32 v64, v2
	v_mov_b32_e32 v65, v2
	v_mov_b32_e32 v66, v2
	v_mov_b32_e32 v67, v2
	v_mov_b32_e32 v68, v2
	v_mov_b32_e32 v69, v2
	v_mov_b32_e32 v70, v2
	v_mov_b32_e32 v71, v2
	v_mov_b32_e32 v72, v2
	v_mov_b32_e32 v73, v2
	v_mov_b32_e32 v82, v2
	v_mov_b32_e32 v83, v2
	v_mov_b32_e32 v84, v2
	v_mov_b32_e32 v85, v2
	v_mov_b32_e32 v86, v2
	v_mov_b32_e32 v87, v2
	v_mov_b32_e32 v88, v2
	v_mov_b32_e32 v89, v2
	v_mov_b32_e32 v98, v2
	v_mov_b32_e32 v99, v2
	v_mov_b32_e32 v100, v2
	v_mov_b32_e32 v101, v2
	v_mov_b32_e32 v102, v2
	v_mov_b32_e32 v103, v2
	v_mov_b32_e32 v104, v2
	v_mov_b32_e32 v105, v2
	v_mov_b32_e32 v114, v2
	v_mov_b32_e32 v115, v2
	v_mov_b32_e32 v116, v2
	v_mov_b32_e32 v117, v2
	v_mov_b32_e32 v118, v2
	v_mov_b32_e32 v119, v2
	v_mov_b32_e32 v120, v2
	v_mov_b32_e32 v121, v2
	v_mov_b32_e32 v74, v2
	v_mov_b32_e32 v75, v2
	v_mov_b32_e32 v76, v2
	v_mov_b32_e32 v77, v2
	v_mov_b32_e32 v78, v2
	v_mov_b32_e32 v79, v2
	v_mov_b32_e32 v80, v2
	v_mov_b32_e32 v81, v2
	v_mov_b32_e32 v90, v2
	v_mov_b32_e32 v91, v2
	v_mov_b32_e32 v92, v2
	v_mov_b32_e32 v93, v2
	v_mov_b32_e32 v94, v2
	v_mov_b32_e32 v95, v2
	v_mov_b32_e32 v96, v2
	v_mov_b32_e32 v97, v2
	v_mov_b32_e32 v106, v2
	v_mov_b32_e32 v107, v2
	v_mov_b32_e32 v108, v2
	v_mov_b32_e32 v109, v2
	v_mov_b32_e32 v110, v2
	v_mov_b32_e32 v111, v2
	v_mov_b32_e32 v112, v2
	v_mov_b32_e32 v113, v2
	v_mov_b32_e32 v122, v2
	v_mov_b32_e32 v123, v2
	v_mov_b32_e32 v124, v2
	v_mov_b32_e32 v125, v2
	v_mov_b32_e32 v126, v2
	v_mov_b32_e32 v127, v2
	v_mov_b32_e32 v128, v2
	v_mov_b32_e32 v129, v2
	.p2align 6

.LBB0_568:
	s_movk_i32 s4, 0x1ff
	s_or_b64 exec, exec, s[2:3]
	v_readlane_b32 s0, v254, 0
	s_mov_b64 s[2:3], s[66:67]
	s_mov_b32 s26, s64
	s_mov_b32 s28, s0
	s_waitcnt vmcnt(0)
	v_mov_b32_e32 v35, v180
	s_mov_b32 s44, s81
	s_waitcnt lgkmcnt(0)
	s_barrier
	s_load_dwordx2 s[34:35], s[2:3], 0x88
	v_readfirstlane_b32 s45, v35
	s_waitcnt lgkmcnt(0)
	s_add_u32 s30, s34, 0x2400000
	s_addc_u32 s31, s35, 0
	s_cmpk_lt_i32 s28, 0x100
	s_cselect_b64 s[36:37], -1, 0
	s_cmpk_gt_i32 s28, 0xff
	s_cbranch_scc1 .LBB0_591
	v_readlane_b32 s6, v254, 17
	v_readlane_b32 s7, v254, 18
	s_lshl_b32 s33, s6, 3
	s_add_u32 s46, s34, 0x100000
	v_cmp_eq_u32_e64 s[6:7], s4, v35
	s_movk_i32 s4, 0x7f
	s_addc_u32 s47, s35, 0
	v_cmp_lt_i32_e64 s[22:23], s4, v35
	s_movk_i32 s4, 0xff
	s_ashr_i32 s29, s28, 31
	v_cmp_lt_i32_e64 s[24:25], s4, v35
	s_lshl_b64 s[4:5], s[28:29], 2
	s_load_dwordx2 s[0:1], s[2:3], 0x18
	s_add_u32 s4, s34, s4
	s_addc_u32 s5, s35, s5
	s_add_u32 s4, s4, 0x212000
	v_lshl_add_u32 v0, v35, 2, s44
	s_addc_u32 s5, s5, 0
	s_ashr_i32 s27, s26, 31
	v_cmp_lt_i32_e64 s[8:9], 0, v35
	v_add_u32_e32 v4, -4, v0
	v_cmp_lt_i32_e64 s[10:11], 1, v35
	v_add_u32_e32 v5, -8, v0
	v_cmp_lt_i32_e64 s[12:13], 3, v35
	v_add_u32_e32 v6, -16, v0
	v_cmp_lt_i32_e64 s[14:15], 7, v35
	v_subrev_u32_e32 v7, 32, v0
	v_cmp_lt_i32_e64 s[16:17], 15, v35
	v_subrev_u32_e32 v8, 64, v0
	v_cmp_lt_i32_e64 s[18:19], 31, v35
	v_add_u32_e32 v9, 0xffffff80, v0
	v_cmp_lt_i32_e64 s[20:21], 63, v35
	v_add_u32_e32 v10, 0xffffff00, v0
	v_add_u32_e32 v11, 0xfffffe00, v0
	v_add_u32_e32 v12, 0xfffffc00, v0
	s_lshl_b64 s[38:39], s[26:27], 2
	s_lshl_b32 s27, s28, 6
	s_lshl_b32 s29, s26, 6
	s_lshl_b32 s48, s28, 9
	s_lshl_b32 s49, s26, 9
	s_mov_b32 s50, s28
	s_branch .LBB0_571
	.p2align 6

.LBB0_593:
	s_andn2_b64 vcc, exec, s[0:1]
	v_and_b32_e32 v34, 63, v35
	s_movk_i32 s38, 0x1ff
	s_cbranch_vccnz .LBB0_598
	v_and_b32_e32 v0, 64, v186
	v_add_u32_e32 v2, 64, v0
	v_xor_b32_e32 v0, 32, v186
	v_cmp_lt_i32_e64 s[0:1], v0, v2
	v_xor_b32_e32 v3, 16, v186
	s_ashr_i32 s7, s6, 31
	v_cndmask_b32_e64 v0, v186, v0, s[0:1]
	v_cmp_lt_i32_e64 s[0:1], v3, v2
	s_lshl_b32 s8, s26, 3
	v_cmp_eq_u32_e32 vcc, 0, v34
	v_cndmask_b32_e64 v3, v186, v3, s[0:1]
	v_lshlrev_b32_e32 v36, 2, v3
	v_xor_b32_e32 v3, 8, v186
	v_cmp_lt_i32_e64 s[0:1], v3, v2
	v_lshlrev_b32_e32 v0, 2, v0
	s_nop 0
	v_cndmask_b32_e64 v3, v186, v3, s[0:1]
	v_lshlrev_b32_e32 v37, 2, v3
	v_xor_b32_e32 v3, 4, v186
	v_cmp_lt_i32_e64 s[0:1], v3, v2
	s_nop 1
	v_cndmask_b32_e64 v3, v186, v3, s[0:1]
	v_lshlrev_b32_e32 v38, 2, v3
	v_xor_b32_e32 v3, 2, v186
	v_cmp_lt_i32_e64 s[0:1], v3, v2
	s_nop 1
	v_cndmask_b32_e64 v3, v186, v3, s[0:1]
	v_lshlrev_b32_e32 v39, 2, v3
	v_xor_b32_e32 v3, 1, v186
	v_cmp_lt_i32_e64 s[0:1], v3, v2
	s_nop 1
	v_cndmask_b32_e64 v2, v186, v3, s[0:1]
	s_lshl_b64 s[0:1], s[6:7], 2
	s_add_u32 s0, s34, s0
	s_addc_u32 s1, s35, s1
	s_add_u32 s10, s0, 0x210000
	s_addc_u32 s11, s1, 0
	s_ashr_i32 s9, s8, 31
	s_lshl_b32 s7, s28, 9
	s_lshl_b32 s0, s27, 6
	s_lshl_b64 s[12:13], s[8:9], 2
	s_add_i32 s9, s7, s0
	s_lshl_b32 s0, s28, 6
	s_lshl_b32 s1, s27, 3
	v_lshlrev_b32_e32 v40, 2, v2
	s_lshl_b32 s16, s26, 9
	s_add_i32 s17, s0, s1
	s_lshl_b32 s18, s26, 6
	s_branch .LBB0_596
	.p2align 6

.LBB0_598:
	v_add_u32_e32 v0, s7, v35
	s_mov_b32 s0, 0x30000
	v_cmp_gt_i32_e32 vcc, s0, v0
	s_and_saveexec_b64 s[0:1], vcc
	s_cbranch_execz .LBB0_609
	s_lshl_b32 s4, s28, 15
	v_lshl_add_u32 v2, v35, 6, s4
	s_lshl_b32 s10, s26, 9
	v_add_u32_e32 v10, 0x700, v2
	s_lshl_b32 s11, s26, 15
	s_mov_b64 s[4:5], 0
	s_branch .LBB0_601
	.p2align 6

.LBB0_609:
	s_or_b64 exec, exec, s[0:1]
	s_andn2_b64 vcc, exec, s[36:37]
	s_cbranch_vccnz .LBB0_698
	v_and_b32_e32 v139, 15, v35
	v_and_b32_e32 v158, 0xff, v35
	s_lshl_b32 s0, s27, 2
	v_lshlrev_b32_e32 v0, 2, v158
	v_lshl_or_b32 v142, s27, 4, v139
	s_mul_hi_i32 s15, s0, 0x2640
	s_waitcnt lgkmcnt(0)
	v_lshl_add_u64 v[2:3], s[34:35], 0, v[0:1]
	s_mov_b64 s[0:1], 0x200000
	v_ashrrev_i32_e32 v143, 31, v142
	s_lshl_b32 s12, s27, 8
	v_lshl_add_u64 v[140:141], v[2:3], 0, s[0:1]
	v_readlane_b32 s0, v254, 17
	v_lshlrev_b64 v[2:3], 9, v[142:143]
	s_ashr_i32 s13, s12, 31
	v_readlane_b32 s1, v254, 18
	s_lshl_b32 s29, s0, 1
	v_lshl_add_u64 v[2:3], s[34:35], 0, v[2:3]
	v_and_b32_e32 v0, 48, v34
	v_lshrrev_b32_e32 v4, 4, v34
	s_cmp_lt_i32 s27, 4
	v_mul_u32_u24_e32 v5, 0x210, v139
	v_lshl_add_u64 v[2:3], v[2:3], 0, v[0:1]
	s_mov_b64 s[0:1], 0x2300000
	v_lshlrev_b32_e32 v138, 3, v4
	s_cselect_b64 s[16:17], -1, 0
	v_add3_u32 v143, s44, v5, v0
	v_lshl_add_u64 v[144:145], v[2:3], 0, s[0:1]
	v_lshl_add_u32 v0, v4, 10, s44
	s_and_b32 s0, s45, 0xffffffc0
	v_lshlrev_b32_e32 v3, 2, v139
	v_and_b32_e32 v2, 7, v35
	v_mul_u32_u24_e32 v4, 0xc00, v4
	v_add3_u32 v159, v0, s0, v3
	v_cvt_f32_ubyte0_e32 v5, v2
	v_add3_u32 v166, v0, v4, v3
	v_lshrrev_b32_e32 v0, 8, v35
	v_mul_f32_e32 v7, 0xc01773da, v5
	s_mov_b32 s0, 0xc2fc0000
	v_mul_i32_i24_e32 v3, 0x210, v0
	v_add_u32_e32 v0, 0x200, v35
	v_mov_b32_e32 v8, 0x42800000
	v_cmp_gt_f32_e32 vcc, s0, v7
	v_lshrrev_b32_e32 v4, 8, v0
	v_ashrrev_i32_e32 v168, 6, v35
	v_cndmask_b32_e32 v7, 0, v8, vcc
	v_mul_i32_i24_e32 v8, 0x210, v4
	v_add_u32_e32 v4, 0x400, v35
	v_lshrrev_b32_e32 v4, 8, v4
	v_mul_i32_i24_e32 v9, 0x210, v4
	v_add_u32_e32 v4, 0x600, v35
	v_lshrrev_b32_e32 v4, 8, v4
	v_mul_i32_i24_e32 v10, 0x210, v4
	v_add_u32_e32 v4, 0x800, v35
	v_lshrrev_b32_e32 v4, 8, v4
	v_mul_i32_i24_e32 v11, 0x210, v4
	v_add_u32_e32 v4, 0xa00, v35
	v_lshrrev_b32_e32 v4, 8, v4
	v_mul_i32_i24_e32 v12, 0x210, v4
	v_add_u32_e32 v4, 0xc00, v35
	v_fmac_f32_e32 v7, 0xc01773da, v5
	v_lshrrev_b32_e32 v4, 8, v4
	v_exp_f32_e32 v5, v7
	v_mul_i32_i24_e32 v13, 0x210, v4
	v_add_u32_e32 v4, 0xe00, v35
	v_lshrrev_b32_e32 v4, 8, v4
	v_lshl_add_u32 v7, v2, 2, s44
	v_not_b32_e32 v2, 63
	v_mul_i32_i24_e32 v14, 0x210, v4
	v_and_b32_e32 v4, 0x3fffffc0, v35
	v_cndmask_b32_e32 v2, 0, v2, vcc
	v_lshl_add_u32 v15, v4, 2, v7
	v_bfe_u32 v4, v168, 2, 2
	v_ldexp_f32 v161, v5, v2
	v_lshlrev_b32_e32 v5, 2, v4
	v_cmp_ne_u32_e32 vcc, 2, v4
	v_ashrrev_i32_e32 v170, 6, v0
	v_and_b32_e32 v0, 0x3fffffc0, v0
	v_cndmask_b32_e32 v5, 4, v5, vcc
	v_cmp_ne_u32_e32 vcc, 1, v4
	v_lshl_add_u32 v7, v0, 2, v7
	v_bfe_u32 v0, v170, 2, 2
	s_add_u32 s33, s34, 0x180000
	v_cndmask_b32_e32 v169, 8, v5, vcc
	v_lshlrev_b32_e32 v4, 2, v0
	v_cmp_ne_u32_e32 vcc, 2, v0
	s_addc_u32 s36, s35, 0
	s_cmp_gt_u32 s45, 63
	v_cndmask_b32_e32 v4, 4, v4, vcc
	v_cmp_ne_u32_e32 vcc, 1, v0
	v_lshlrev_b32_e32 v0, 12, v139
	s_mov_b64 s[0:1], 0x2100000
	v_cndmask_b32_e32 v171, 8, v4, vcc
	v_lshl_add_u64 v[4:5], s[34:35], 0, v[0:1]
	s_cselect_b64 s[18:19], -1, 0
	v_lshl_add_u64 v[146:147], v[4:5], 0, s[0:1]
	s_lshl_b64 s[0:1], s[12:13], 1
	s_add_u32 s0, s34, s0
	v_and_or_b32 v0, v35, 48, v0
	s_addc_u32 s1, s35, s1
	v_lshl_add_u32 v6, v158, 1, s44
	v_lshlrev_b32_e32 v2, 6, v34
	v_lshl_add_u64 v[4:5], s[0:1], 0, v[0:1]
	s_mov_b64 s[0:1], 0x2100040
	s_mul_i32 s14, s27, 0x9900
	v_cmp_gt_u32_e64 s[6:7], 16, v34
	v_cmp_gt_u32_e64 s[8:9], 8, v34
	v_lshl_add_u32 v167, v35, 2, s44
	v_lshl_add_u64 v[148:149], v[4:5], 0, s[0:1]
	v_add_u32_e32 v172, v6, v3
	v_add_u32_e32 v173, v6, v8
	v_add_u32_e32 v174, v6, v9
	v_add_u32_e32 v175, v6, v10
	v_add_u32_e32 v176, v6, v11
	v_add_u32_e32 v177, v6, v12
	v_add_u32_e32 v178, v6, v13
	v_add_u32_e32 v179, v6, v14
	v_lshlrev_b32_e32 v150, 1, v2
	v_lshlrev_b32_e32 v152, 1, v34
	v_add_u32_e32 v197, 0x6000, v15
	v_add_u32_e32 v198, 0x6000, v7
	s_branch .LBB0_612
	.p2align 6

.Lattn_noprio:
	v_mov_b32_e32 v161, v180
	v_writelane_b32 v254, s0, 23
	s_mov_b32 s33, s81
	s_nop 0
	v_writelane_b32 v254, s1, 24
	s_mov_b32 s1, s64
	v_readlane_b32 s0, v254, 0
	s_mov_b32 s3, s0
	s_cmpk_gt_i32 s3, 0xff
	v_writelane_b32 v254, s1, 25
	v_readfirstlane_b32 s0, v161
	s_cbranch_scc1 .LBB0_1018
	s_ashr_i32 s1, s0, 6
	s_lshl_b32 s2, s1, 5
	v_writelane_b32 v254, s2, 26
	s_add_i32 s27, s33, 0x1db00
	s_lshl_b32 s2, s1, 2
	s_add_i32 s28, s33, 0x1db40
	s_add_i32 s2, s27, s2
	s_cmp_lt_u32 s0, 64
	v_writelane_b32 v254, s2, 27
	s_cselect_b64 s[4:5], -1, 0
	v_writelane_b32 v254, s4, 28
	s_add_i32 s0, s33, 0x1db20
	s_add_i32 s2, s33, 0xdb00
	v_writelane_b32 v254, s5, 29
	v_writelane_b32 v254, s0, 30
	s_add_i32 s0, s33, 0x1db08
	v_writelane_b32 v254, s0, 31
	s_add_i32 s0, s33, 0x1db28
	v_writelane_b32 v254, s0, 32
	s_add_i32 s0, s33, 0x1db10
	v_writelane_b32 v254, s0, 33
	s_add_i32 s0, s33, 0x1db30
	v_writelane_b32 v254, s0, 34
	s_add_i32 s0, s33, 0x1db18
	v_writelane_b32 v254, s0, 35
	s_add_i32 s0, s33, 0x1db38
	v_writelane_b32 v254, s0, 36
	s_add_i32 s0, s33, 0x1df08
	v_writelane_b32 v254, s0, 37
	s_add_i32 s0, s33, 0x1df0c
	v_writelane_b32 v254, s0, 38
	s_lshl_b32 s0, s1, 3
	s_mulk_i32 s1, 0x1020
	v_writelane_b32 v254, s2, 39
	s_add_i32 s1, s2, s1
	v_writelane_b32 v254, s1, 40
	v_writelane_b32 v254, s0, 41
	s_addk_i32 s0, 0x185
	v_writelane_b32 v254, s0, 42
	v_writelane_b32 v254, s27, 43
	s_add_i32 s29, s33, 0x1df00
	v_writelane_b32 v254, s28, 44
	s_add_i32 s92, s33, 0x1df04
	v_writelane_b32 v254, s29, 45
	s_branch .LBB0_745
	.p2align 6

.LBB0_745:
	s_and_b32 s15, s3, 15
	s_ashr_i32 s14, s3, 4
	v_writelane_b32 v254, s3, 46
	s_xor_b32 s16, s15, 31
	s_mov_b64 s[2:3], -1
	s_branch .LBB0_747
	.p2align 6

.LBB0_786:
	v_lshl_add_u64 v[168:169], s[0:1], 0, v[0:1]
	v_cmp_gt_u32_e32 vcc, 32, v21
	v_mov_b32_e32 v0, 0x3f80
	s_mov_b32 s0, 0x5040100
	v_cndmask_b32_e32 v0, 0, v0, vcc
	v_mov_b32_e32 v14, v1
	v_mov_b32_e32 v15, v1
	s_waitcnt lgkmcnt(0)
	s_barrier
	v_mul_u32_u24_e32 v173, 0x90, v20
	v_perm_b32 v148, v0, v0, s0
	v_mov_b32_e32 v0, v1
	v_mov_b32_e32 v2, v1
	v_mov_b32_e32 v3, v1
	v_mov_b32_e32 v4, v1
	v_mov_b32_e32 v5, v1
	v_mov_b32_e32 v6, v1
	v_mov_b32_e32 v7, v1
	v_mov_b32_e32 v8, v1
	v_mov_b32_e32 v9, v1
	v_mov_b32_e32 v10, v1
	v_mov_b32_e32 v11, v1
	v_mov_b32_e32 v12, v1
	v_mov_b32_e32 v13, v1
	v_mov_b64_e32 v[50:51], v[14:15]
	v_mov_b64_e32 v[34:35], v[14:15]
	s_pack_ll_b32_b16 s0, 0, 0
	v_mov_b64_e32 v[48:49], v[12:13]
	v_mov_b64_e32 v[46:47], v[10:11]
	v_mov_b64_e32 v[44:45], v[8:9]
	v_mov_b64_e32 v[42:43], v[6:7]
	v_mov_b64_e32 v[40:41], v[4:5]
	v_mov_b64_e32 v[38:39], v[2:3]
	v_mov_b64_e32 v[36:37], v[0:1]
	v_mov_b64_e32 v[32:33], v[12:13]
	v_mov_b64_e32 v[30:31], v[10:11]
	v_mov_b64_e32 v[28:29], v[8:9]
	v_mov_b64_e32 v[26:27], v[6:7]
	v_mov_b64_e32 v[24:25], v[4:5]
	v_mov_b64_e32 v[22:23], v[2:3]
	v_mov_b64_e32 v[20:21], v[0:1]
	v_mov_b64_e32 v[18:19], v[14:15]
	s_mov_b32 s13, 4
	v_mov_b32_e32 v149, s0
	v_mov_b32_e32 v150, s0
	v_mov_b32_e32 v151, s0
	v_lshlrev_b32_e32 v158, 2, v153
	v_add3_u32 v174, s33, v173, v156
	s_mov_b32 s17, 0
	v_mov_b32_e32 v86, 0
	s_mov_b32 s19, s92
	v_mov_b64_e32 v[16:17], v[12:13]
	v_mov_b64_e32 v[14:15], v[10:11]
	v_mov_b64_e32 v[12:13], v[8:9]
	v_mov_b64_e32 v[10:11], v[6:7]
	v_mov_b64_e32 v[8:9], v[4:5]
	v_mov_b64_e32 v[6:7], v[2:3]
	v_mov_b64_e32 v[4:5], v[0:1]
	v_and_b32_e32 v52, 31, v186
	v_or_b32_e32 v53, 0, v158
	v_cmp_le_u32_e64 s[36:37], v53, v52
	v_or_b32_e32 v53, 1, v158
	v_cmp_le_u32_e64 s[38:39], v53, v52
	v_or_b32_e32 v53, 2, v158
	v_cmp_le_u32_e64 s[40:41], v53, v52
	v_or_b32_e32 v53, 3, v158
	v_cmp_le_u32_e64 s[42:43], v53, v52
	v_or_b32_e32 v53, 8, v158
	v_cmp_le_u32_e64 s[44:45], v53, v52
	v_or_b32_e32 v53, 9, v158
	v_cmp_le_u32_e64 s[46:47], v53, v52
	v_or_b32_e32 v53, 10, v158
	v_cmp_le_u32_e64 s[48:49], v53, v52
	v_or_b32_e32 v53, 11, v158
	v_cmp_le_u32_e64 s[50:51], v53, v52
	v_or_b32_e32 v53, 16, v158
	v_cmp_le_u32_e64 s[52:53], v53, v52
	v_or_b32_e32 v53, 17, v158
	v_cmp_le_u32_e64 s[54:55], v53, v52
	v_or_b32_e32 v53, 18, v158
	v_cmp_le_u32_e64 s[56:57], v53, v52
	v_or_b32_e32 v53, 19, v158
	v_cmp_le_u32_e64 s[58:59], v53, v52
	v_or_b32_e32 v53, 24, v158
	v_cmp_le_u32_e64 s[60:61], v53, v52
	v_or_b32_e32 v53, 25, v158
	v_cmp_le_u32_e64 s[62:63], v53, v52
	v_or_b32_e32 v53, 26, v158
	v_cmp_le_u32_e64 s[70:71], v53, v52
	v_or_b32_e32 v53, 27, v158
	v_cmp_le_u32_e64 s[72:73], v53, v52
	s_branch .LBB0_790
	.p2align 6
.LBB0_787:
	s_or_b64 exec, exec, s[0:1]
	.p2align 6

.Lfox_noresc2:
	.p2align 6

.LBB0_822:
	v_readlane_b32 s0, v254, 46
	s_ashr_i32 s1, s0, 6
	v_writelane_b32 v254, s1, 47
	s_and_b32 s0, s0, 63
	v_writelane_b32 v254, s0, 48
	s_xor_b32 s0, s0, 0x7f
	v_writelane_b32 v254, s0, 49
	s_add_u32 s0, s30, 0x180000
	v_writelane_b32 v254, s0, 50
	v_writelane_b32 v254, s30, 51
	s_addc_u32 s0, s31, 0
	s_nop 0
	v_writelane_b32 v254, s31, 52
	v_writelane_b32 v254, s0, 53
	s_mov_b64 s[0:1], -1
	s_branch .LBB0_824
	.p2align 6

.LBB0_827:
	s_or_b64 exec, exec, s[2:3]
	s_xor_b64 s[0:1], s[0:1], -1
	v_writelane_b32 v254, s0, 56
	v_and_b32_e32 v211, 63, v214
	v_and_b32_e32 v212, 31, v214
	v_writelane_b32 v254, s1, 57
	s_movk_i32 s0, 0x100
	v_ashrrev_i32_e32 v167, 31, v166
	v_lshlrev_b32_e32 v169, 6, v215
	v_cmp_gt_i32_e32 vcc, s0, v214
	s_and_saveexec_b64 s[0:1], vcc
	v_lshl_add_u32 v0, v214, 2, s27
	ds_write_b32 v0, v1
	s_or_b64 exec, exec, s[0:1]
	s_mov_b32 s16, 1
	v_ashrrev_i32_e32 v100, 3, v214
	v_mul_u32_u24_e32 v206, 0x90, v212
	s_movk_i32 s0, 0x90
	s_waitcnt lgkmcnt(0)
	s_barrier
	s_cmp_lt_i32 s16, 1
	v_lshlrev_b32_e32 v213, 4, v214
	v_mul_lo_u32 v207, v100, s0
	v_add3_u32 v208, s33, v206, v168
	s_cbranch_scc1 .LBB0_891
	s_lshl_b32 s0, s84, 2
	s_addk_i32 s0, 0x42
	s_ashr_i32 s95, s94, 31
	s_ashr_i32 s17, s0, 6
	s_lshl_b64 s[0:1], s[94:95], 16
	v_readlane_b32 s2, v254, 50
	s_add_u32 s6, s2, s0
	v_readlane_b32 s0, v254, 53
	v_ashrrev_i32_e32 v101, 31, v100
	s_addc_u32 s7, s0, s1
	v_lshlrev_b64 v[2:3], 7, v[100:101]
	v_lshlrev_b32_e32 v0, 4, v214
	v_lshl_add_u64 v[4:5], s[6:7], 0, v[2:3]
	v_and_b32_e32 v102, 0x70, v0
	v_mov_b32_e32 v103, v1
	s_mov_b64 s[4:5], 0x2000
	s_add_u32 s8, s6, 0x40000
	v_lshl_add_u64 v[104:105], v[4:5], 0, v[102:103]
	v_lshl_add_u64 v[4:5], v[2:3], 0, s[4:5]
	s_addc_u32 s9, s7, 0
	v_lshl_add_u64 v[6:7], s[6:7], 0, v[4:5]
	v_lshl_add_u64 v[106:107], v[6:7], 0, v[102:103]
	v_lshl_add_u64 v[6:7], v[2:3], 0, s[68:69]
	v_lshl_add_u64 v[2:3], s[8:9], 0, v[2:3]
	s_cmp_gt_i32 s17, 0
	v_lshl_add_u64 v[112:113], v[2:3], 0, v[102:103]
	v_lshl_add_u64 v[2:3], s[8:9], 0, v[4:5]
	s_cselect_b64 s[0:1], -1, 0
	s_cmp_lg_u32 s17, 1
	v_lshl_add_u64 v[114:115], v[2:3], 0, v[102:103]
	v_lshl_add_u64 v[2:3], s[8:9], 0, v[6:7]
	v_lshl_add_u64 v[118:119], s[8:9], 0, v[102:103]
	v_and_b32_e32 v0, 35, v214
	v_readlane_b32 s8, v254, 40
	s_cselect_b64 s[2:3], -1, 0
	s_cmp_gt_u32 s17, 2
	v_lshl_add_u64 v[8:9], s[6:7], 0, v[6:7]
	v_lshl_add_u64 v[110:111], s[6:7], 0, v[102:103]
	v_cmp_eq_u32_e64 s[6:7], 0, v0
	v_mov_b32_e32 v0, s8
	s_movk_i32 s8, 0x204
	s_mov_b32 s18, 0
	v_add3_u32 v101, s33, v207, v102
	s_cselect_b64 s[4:5], -1, 0
	v_lshl_add_u64 v[108:109], v[8:9], 0, v[102:103]
	v_lshlrev_b32_e32 v216, 6, v204
	v_lshl_add_u64 v[116:117], v[2:3], 0, v[102:103]
	v_add_u32_e32 v103, 0x100, v100
	v_mad_u32_u24 v217, v209, s8, v0
	s_branch .LBB0_832
	.p2align 6

.LBB0_832:
	s_andn2_b64 vcc, exec, s[0:1]
	s_mov_b64 s[8:9], -1
	s_cbranch_vccnz .LBB0_882
	global_load_dwordx4 v[50:53], v[104:105], off
	v_cndmask_b32_e64 v0, 0, 1, s[2:3]
	v_cmp_ne_u32_e64 s[8:9], 1, v0
	s_andn2_b64 vcc, exec, s[2:3]
	s_cbranch_vccnz .LBB0_883
	global_load_dwordx4 v[54:57], v[106:107], off
	s_and_b64 vcc, exec, s[8:9]
	s_waitcnt vmcnt(1)
	ds_write_b128 v101, v[50:53]
	s_cbranch_vccz .LBB0_884
	.p2align 6
.LBB0_835:
	v_cndmask_b32_e64 v0, 0, 1, s[4:5]
	v_cmp_ne_u32_e64 s[10:11], 1, v0
	s_andn2_b64 vcc, exec, s[4:5]
	s_cbranch_vccnz .LBB0_837
	.p2align 6
.LBB0_836:
	global_load_dwordx4 v[50:53], v[108:109], off
	.p2align 6
.LBB0_837:
	s_waitcnt lgkmcnt(0)
	s_barrier
	v_mov_b32_e32 v2, v1
	v_mov_b32_e32 v3, v1
	v_mov_b32_e32 v4, v1
	v_mov_b32_e32 v5, v1
	v_mov_b32_e32 v6, v1
	v_mov_b32_e32 v7, v1
	v_mov_b32_e32 v8, v1
	v_mov_b32_e32 v9, v1
	v_mov_b32_e32 v10, v1
	v_mov_b32_e32 v11, v1
	v_mov_b32_e32 v12, v1
	v_mov_b32_e32 v13, v1
	v_mov_b32_e32 v14, v1
	v_mov_b32_e32 v15, v1
	v_mov_b32_e32 v0, v1
	v_mov_b64_e32 v[16:17], v[14:15]
	s_mov_b32 s19, 0
	v_mov_b32_e32 v60, 0
	s_mov_b32 s20, 4
	s_movk_i32 s21, 0x80f
	v_mov_b32_e32 v58, v103
	v_mov_b32_e32 v61, 0
	v_mov_b64_e32 v[14:15], v[12:13]
	v_mov_b64_e32 v[12:13], v[10:11]
	v_mov_b64_e32 v[10:11], v[8:9]
	v_mov_b64_e32 v[8:9], v[6:7]
	v_mov_b64_e32 v[6:7], v[4:5]
	v_mov_b64_e32 v[4:5], v[2:3]
	v_mov_b64_e32 v[2:3], v[0:1]
	s_branch .LBB0_839
	.p2align 6
.LBB0_838:
	s_waitcnt lgkmcnt(0)
	s_barrier
	s_add_i32 s20, s20, 2
	s_addk_i32 s21, 0x800
	v_add_f32_e32 v0, v18, v0
	s_cmp_ge_i32 s23, s17
	v_add_f32_e32 v60, v60, v0
	v_add_u32_e32 v58, 0x80, v58
	s_cselect_b64 s[14:15], -1, 0
	s_and_b64 vcc, exec, s[14:15]
	s_cbranch_vccnz .LBB0_857
	.p2align 6

.LBB0_857:
	global_load_dwordx4 v[82:85], v[104:105], off
	global_load_dwordx4 v[86:89], v[112:113], off
	s_and_b64 vcc, exec, s[8:9]
	s_cbranch_vccnz .LBB0_885
	global_load_dwordx4 v[90:93], v[106:107], off
	global_load_dwordx4 v[94:97], v[114:115], off
	s_and_b64 vcc, exec, s[8:9]
	s_waitcnt vmcnt(3)
	ds_write_b128 v101, v[82:85]
	s_waitcnt vmcnt(2)
	ds_write_b128 v101, v[86:89] offset:9216
	s_cbranch_vccz .LBB0_886
	.p2align 6
.LBB0_859:
	s_and_b64 vcc, exec, s[10:11]
	s_cbranch_vccnz .LBB0_861
	.p2align 6
.LBB0_860:
	global_load_dwordx4 v[82:85], v[108:109], off
	global_load_dwordx4 v[86:89], v[116:117], off
	.p2align 6
.LBB0_861:
	v_div_scale_f32 v0, s[8:9], v60, v60, 1.0
	v_rcp_f32_e32 v2, v0
	v_div_scale_f32 v3, vcc, 1.0, v60, 1.0
	s_waitcnt lgkmcnt(0)
	s_barrier
	v_fma_f32 v4, -v0, v2, 1.0
	v_fmac_f32_e32 v2, v4, v2
	v_mul_f32_e32 v4, v3, v2
	v_fma_f32 v5, -v0, v4, v3
	v_fmac_f32_e32 v4, v5, v2
	v_fma_f32 v0, -v0, v4, v3
	v_div_fmas_f32 v0, v0, v2, v4
	v_div_fixup_f32 v0, v0, v60, 1.0
	v_cmp_lt_f32_e32 vcc, 0, v60
	v_xor_b32_e32 v34, 0x80000000, v61
	v_mov_b32_e32 v2, 0
	v_cndmask_b32_e32 v120, 0, v0, vcc
	v_mov_b32_e32 v35, v34
	v_mov_b32_e32 v36, v34
	v_mov_b32_e32 v37, v34
	v_mov_b32_e32 v38, v34
	v_mov_b32_e32 v39, v34
	v_mov_b32_e32 v40, v34
	v_mov_b32_e32 v41, v34
	v_mov_b32_e32 v42, v34
	v_mov_b32_e32 v43, v34
	v_mov_b32_e32 v44, v34
	v_mov_b32_e32 v45, v34
	v_mov_b32_e32 v46, v34
	v_mov_b32_e32 v47, v34
	v_mov_b32_e32 v48, v34
	v_mov_b32_e32 v49, v34
	v_mov_b32_e32 v121, v120
	s_mov_b32 s14, 0
	s_mov_b32 s19, 4
	s_movk_i32 s15, 0x80f
	v_mov_b32_e32 v0, v217
	v_mov_b32_e32 v122, v103
	v_mov_b32_e32 v3, v2
	v_mov_b32_e32 v4, v2
	v_mov_b32_e32 v5, v2
	v_mov_b32_e32 v6, v2
	v_mov_b32_e32 v7, v2
	v_mov_b32_e32 v8, v2
	v_mov_b32_e32 v9, v2
	v_mov_b32_e32 v10, v2
	v_mov_b32_e32 v11, v2
	v_mov_b32_e32 v12, v2
	v_mov_b32_e32 v13, v2
	v_mov_b32_e32 v14, v2
	v_mov_b32_e32 v15, v2
	v_mov_b32_e32 v16, v2
	v_mov_b32_e32 v17, v2
	v_mov_b32_e32 v18, v2
	v_mov_b32_e32 v19, v2
	v_mov_b32_e32 v20, v2
	v_mov_b32_e32 v21, v2
	v_mov_b32_e32 v22, v2
	v_mov_b32_e32 v23, v2
	v_mov_b32_e32 v24, v2
	v_mov_b32_e32 v25, v2
	v_mov_b32_e32 v26, v2
	v_mov_b32_e32 v27, v2
	v_mov_b32_e32 v28, v2
	v_mov_b32_e32 v29, v2
	v_mov_b32_e32 v30, v2
	v_mov_b32_e32 v31, v2
	v_mov_b32_e32 v32, v2
	v_mov_b32_e32 v33, v2
	.p2align 6

.LBB0_893:
	v_and_b32_e32 v0, 7, v214
	s_andn2_b64 vcc, exec, s[0:1]
	v_lshlrev_b32_e32 v170, 4, v0
	s_cbranch_vccnz .LBB0_937
	v_lshlrev_b32_e32 v40, 1, v214
	s_movk_i32 s0, 0x204
	v_lshlrev_b32_e32 v38, 4, v100
	v_and_b32_e32 v40, 12, v40
	v_mul_lo_u32 v39, v100, s0
	v_add3_u32 v38, s27, v38, v40
	v_lshlrev_b32_e32 v40, 6, v0
	v_add3_u32 v39, s33, v39, v40
	v_or_b32_e32 v40, 1, v170
	v_cmp_ne_u32_e64 s[10:11], s84, v40
	v_or_b32_e32 v40, 2, v170
	v_cmp_ne_u32_e64 s[8:9], s84, v40
	v_cmp_lt_i32_e64 s[30:31], s84, v40
	v_or_b32_e32 v40, 3, v170
	v_cmp_ne_u32_e64 s[12:13], s84, v40
	v_cmp_lt_i32_e64 s[36:37], s84, v40
	v_or_b32_e32 v40, 4, v170
	v_cmp_ne_u32_e64 s[14:15], s84, v40
	v_cmp_lt_i32_e64 s[40:41], s84, v40
	v_or_b32_e32 v40, 5, v170
	v_cmp_lt_u32_e64 s[28:29], 1, v0
	v_cmp_ne_u32_e64 s[16:17], s84, v40
	v_cmp_lt_i32_e64 s[44:45], s84, v40
	v_or_b32_e32 v40, 6, v170
	v_writelane_b32 v255, s28, 0
	v_cmp_ne_u32_e64 s[18:19], s84, v40
	v_cmp_lt_i32_e64 s[48:49], s84, v40
	v_or_b32_e32 v40, 7, v170
	v_writelane_b32 v255, s29, 1
	v_cmp_lt_u32_e64 s[28:29], 2, v0
	v_cmp_ne_u32_e64 s[20:21], s84, v40
	v_cmp_lt_i32_e64 s[52:53], s84, v40
	v_or_b32_e32 v40, 8, v170
	v_writelane_b32 v255, s28, 2
	v_cmp_ne_u32_e64 s[38:39], s84, v40
	v_cmp_lt_i32_e64 s[42:43], s84, v40
	v_or_b32_e32 v40, 9, v170
	v_writelane_b32 v255, s29, 3
	v_cmp_lt_u32_e64 s[28:29], 3, v0
	v_cmp_ne_u32_e64 s[46:47], s84, v40
	v_cmp_lt_i32_e64 s[56:57], s84, v40
	v_or_b32_e32 v40, 10, v170
	v_writelane_b32 v255, s28, 4
	v_cmp_ne_u32_e64 s[50:51], s84, v40
	v_cmp_lt_i32_e64 s[60:61], s84, v40
	v_or_b32_e32 v40, 11, v170
	v_writelane_b32 v255, s29, 5
	v_cmp_lt_u32_e64 s[28:29], 4, v0
	v_cmp_ne_u32_e64 s[54:55], s84, v40
	v_cmp_lt_i32_e64 s[64:65], s84, v40
	v_or_b32_e32 v40, 12, v170
	v_writelane_b32 v255, s28, 6
	v_writelane_b32 v254, s80, 58
	v_cmp_ne_u32_e64 s[58:59], s84, v40
	v_cmp_lt_i32_e64 s[68:69], s84, v40
	v_or_b32_e32 v40, 13, v170
	v_writelane_b32 v255, s29, 7
	v_cmp_lt_u32_e64 s[28:29], 5, v0
	v_writelane_b32 v254, s81, 59
	v_cmp_eq_u32_e64 s[0:1], 0, v0
	v_cmp_ne_u32_e64 s[66:67], s84, v40
	v_cmp_lt_i32_e64 s[62:63], s84, v40
	v_or_b32_e32 v40, 14, v170
	v_writelane_b32 v255, s28, 8
	v_writelane_b32 v254, s0, 60
	v_cmp_ne_u32_e64 s[22:23], s84, v40
	v_cmp_lt_i32_e64 s[26:27], s84, v40
	v_or_b32_e32 v40, 15, v170
	v_writelane_b32 v255, s29, 9
	v_cmp_eq_u32_e64 s[28:29], 7, v0
	s_cmp_gt_i32 s84, 15
	v_writelane_b32 v254, s1, 61
	v_cmp_ne_u32_e32 vcc, 0, v0
	v_cmp_ne_u32_e64 s[0:1], s84, v170
	v_cmp_ge_i32_e64 s[2:3], s84, v40
	v_writelane_b32 v255, s28, 10
	s_cselect_b64 s[4:5], -1, 0
	s_and_b64 s[6:7], vcc, s[0:1]
	v_cmp_ge_i32_e64 s[0:1], s84, v170
	v_cmp_gt_i32_e64 s[82:83], s84, v170
	v_writelane_b32 v254, s2, 62
	v_writelane_b32 v255, s29, 11
	v_cmp_ne_u32_e64 s[24:25], s84, v40
	v_writelane_b32 v254, s3, 63
	v_cmp_lt_i32_e64 s[2:3], s84, v40
	v_writelane_b32 v255, s0, 12
	v_cndmask_b32_e64 v41, 0, 2, s[82:83]
	v_cndmask_b32_e64 v42, 8, 0, s[36:37]
	v_cndmask_b32_e64 v40, 0, 1, s[0:1]
	v_or_b32_e32 v40, v41, v40
	v_cndmask_b32_e64 v41, 4, 0, s[30:31]
	v_writelane_b32 v255, s1, 13
	v_or3_b32 v40, v40, v41, v42
	v_cndmask_b32_e64 v41, 16, 0, s[40:41]
	v_cndmask_b32_e64 v42, 32, 0, s[44:45]
	v_or3_b32 v40, v40, v41, v42
	v_cndmask_b32_e64 v41, 64, 0, s[48:49]
	v_cndmask_b32_e64 v42, v188, 0, s[52:53]
	v_writelane_b32 v255, s2, 14
	v_or3_b32 v40, v40, v41, v42
	v_cndmask_b32_e64 v41, v189, 0, s[42:43]
	v_cndmask_b32_e64 v42, v190, 0, s[56:57]
	v_writelane_b32 v255, s3, 15
	v_or3_b32 v40, v40, v41, v42
	v_cndmask_b32_e64 v41, v191, 0, s[60:61]
	v_cndmask_b32_e64 v42, v192, 0, s[64:65]
	v_writelane_b32 v255, s22, 16
	v_or3_b32 v40, v40, v41, v42
	v_cndmask_b32_e64 v41, v193, 0, s[68:69]
	v_cndmask_b32_e64 v42, v194, 0, s[62:63]
	v_writelane_b32 v255, s23, 17
	v_or3_b32 v40, v40, v41, v42
	v_cndmask_b32_e64 v41, v195, 0, s[26:27]
	v_cndmask_b32_e64 v42, v196, 0, s[2:3]
	v_writelane_b32 v255, s66, 18
	v_or3_b32 v40, v40, v41, v42
	v_and_or_b32 v41, v214, 56, v197
	v_writelane_b32 v255, s67, 19
	v_lshlrev_b32_e32 v41, 2, v41
	v_writelane_b32 v255, s24, 20
	v_and_b32_e32 v37, 16, v213
	s_mov_b32 s73, 0
	v_or_b32_e32 v42, 4, v41
	v_or_b32_e32 v43, 8, v41
	v_or_b32_e32 v44, 12, v41
	v_or_b32_e32 v45, 16, v41
	v_or_b32_e32 v46, 20, v41
	v_or_b32_e32 v47, 24, v41
	v_writelane_b32 v255, s25, 21
	s_branch .LBB0_896
	.p2align 6

.LBB0_896:
	s_waitcnt lgkmcnt(0)
	v_mov_b32_e32 v48, 0x49742400
	v_mov_b32_e32 v49, 0x49742400
	s_and_saveexec_b64 s[0:1], s[6:7]
	ds_read_b32 v49, v39 offset:56064
	s_or_b64 exec, exec, s[0:1]
	s_and_saveexec_b64 s[0:1], s[10:11]
	ds_read_b32 v48, v39 offset:56068
	s_or_b64 exec, exec, s[0:1]
	v_mov_b32_e32 v50, 0x49742400
	v_mov_b32_e32 v51, 0x49742400
	s_and_saveexec_b64 s[0:1], s[8:9]
	ds_read_b32 v51, v39 offset:56072
	s_or_b64 exec, exec, s[0:1]
	s_and_saveexec_b64 s[0:1], s[12:13]
	ds_read_b32 v50, v39 offset:56076
	s_or_b64 exec, exec, s[0:1]
	v_mov_b32_e32 v52, 0x49742400
	v_mov_b32_e32 v53, 0x49742400
	s_and_saveexec_b64 s[0:1], s[14:15]
	ds_read_b32 v53, v39 offset:56080
	s_or_b64 exec, exec, s[0:1]
	s_and_saveexec_b64 s[0:1], s[16:17]
	ds_read_b32 v52, v39 offset:56084
	s_or_b64 exec, exec, s[0:1]
	v_mov_b32_e32 v54, 0x49742400
	v_mov_b32_e32 v55, 0x49742400
	s_and_saveexec_b64 s[0:1], s[18:19]
	ds_read_b32 v55, v39 offset:56088
	s_or_b64 exec, exec, s[0:1]
	s_and_saveexec_b64 s[0:1], s[20:21]
	ds_read_b32 v54, v39 offset:56092
	s_or_b64 exec, exec, s[0:1]
	v_mov_b32_e32 v56, 0x49742400
	v_mov_b32_e32 v57, 0x49742400
	s_and_saveexec_b64 s[0:1], s[38:39]
	ds_read_b32 v57, v39 offset:56096
	s_or_b64 exec, exec, s[0:1]
	s_and_saveexec_b64 s[0:1], s[46:47]
	ds_read_b32 v56, v39 offset:56100
	s_or_b64 exec, exec, s[0:1]
	v_mov_b32_e32 v58, 0x49742400
	v_mov_b32_e32 v59, 0x49742400
	s_and_saveexec_b64 s[0:1], s[50:51]
	ds_read_b32 v59, v39 offset:56104
	s_or_b64 exec, exec, s[0:1]
	s_and_saveexec_b64 s[0:1], s[54:55]
	ds_read_b32 v58, v39 offset:56108
	s_or_b64 exec, exec, s[0:1]
	v_mov_b32_e32 v60, 0x49742400
	v_mov_b32_e32 v62, 0x49742400
	s_and_saveexec_b64 s[0:1], s[58:59]
	ds_read_b32 v62, v39 offset:56112
	s_or_b64 exec, exec, s[0:1]
	s_and_saveexec_b64 s[0:1], s[66:67]
	ds_read_b32 v60, v39 offset:56116
	s_or_b64 exec, exec, s[0:1]
	v_mov_b32_e32 v61, 0x49742400
	v_mov_b32_e32 v63, 0x49742400
	s_and_saveexec_b64 s[0:1], s[22:23]
	s_cbranch_execz .LBB0_932
	ds_read_b32 v63, v39 offset:56120
	s_or_b64 exec, exec, s[0:1]
	s_and_saveexec_b64 s[0:1], s[24:25]
	s_cbranch_execnz .LBB0_933
	.p2align 6
.LBB0_926:
	s_or_b64 exec, exec, s[0:1]
	s_andn2_b64 vcc, exec, s[4:5]
	v_mov_b32_e32 v67, v40
	s_cbranch_vccnz .LBB0_934
	.p2align 6

.LBB0_937:
	s_mov_b64 s[0:1], 0x2610
	v_lshl_add_u64 v[172:173], v[34:35], 0, s[0:1]
	s_waitcnt vmcnt(0)
	v_lshlrev_b32_e32 v34, 16, v36
	v_mul_f32_e32 v34, 0xbfb8aa3b, v34
	v_exp_f32_e32 v34, v34
	v_add_u32_e32 v215, s33, v37
	s_mov_b32 s87, s81
	v_add_u32_e32 v178, 0xdb00, v215
	v_add_f32_e32 v34, 1.0, v34
	v_div_scale_f32 v35, s[0:1], v34, v34, 1.0
	v_rcp_f32_e32 v36, v35
	v_div_scale_f32 v38, vcc, 1.0, v34, 1.0
	v_readlane_b32 s0, v254, 28
	v_fma_f32 v39, -v35, v36, 1.0
	v_fmac_f32_e32 v36, v39, v36
	v_mul_f32_e32 v39, v38, v36
	v_fma_f32 v40, -v35, v39, v38
	v_fmac_f32_e32 v39, v40, v36
	v_fma_f32 v35, -v35, v39, v38
	v_div_fmas_f32 v35, v35, v36, v39
	v_div_fixup_f32 v34, v35, v34, 1.0
	v_readlane_b32 s1, v254, 29
	v_mul_f32_e32 v20, v20, v34
	v_mul_f32_e32 v21, v21, v34
	v_mul_f32_e32 v18, v18, v34
	v_mul_f32_e32 v19, v19, v34
	v_mul_f32_e32 v16, v16, v34
	v_mul_f32_e32 v17, v17, v34
	v_mul_f32_e32 v14, v14, v34
	v_mul_f32_e32 v15, v15, v34
	v_mul_f32_e32 v12, v12, v34
	v_mul_f32_e32 v13, v13, v34
	v_mul_f32_e32 v10, v10, v34
	v_mul_f32_e32 v11, v11, v34
	v_mul_f32_e32 v8, v8, v34
	v_mul_f32_e32 v9, v9, v34
	v_mul_f32_e32 v6, v6, v34
	v_mul_f32_e32 v7, v7, v34
	v_add_u32_e32 v214, 0x17b00, v215
	v_add_u32_e32 v213, 0x19b00, v215
	v_add_u32_e32 v179, 0x1bb00, v215
	s_and_b64 vcc, exec, s[0:1]
	v_mul_f32_e32 v32, v32, v34
	v_mul_f32_e32 v33, v33, v34
	v_mul_f32_e32 v30, v30, v34
	v_mul_f32_e32 v31, v31, v34
	v_mul_f32_e32 v28, v28, v34
	v_mul_f32_e32 v29, v29, v34
	v_mul_f32_e32 v26, v26, v34
	v_mul_f32_e32 v27, v27, v34
	v_mul_f32_e32 v24, v24, v34
	v_mul_f32_e32 v25, v25, v34
	v_mul_f32_e32 v22, v22, v34
	v_mul_f32_e32 v23, v23, v34
	v_mul_f32_e32 v4, v4, v34
	v_mul_f32_e32 v5, v5, v34
	v_mul_f32_e32 v2, v2, v34
	v_mul_f32_e32 v3, v3, v34
	s_waitcnt lgkmcnt(0)
	s_barrier
	ds_write_b128 v215, v[18:21] offset:56064
	ds_write_b128 v178, v[2:5] offset:32768
	ds_write_b128 v215, v[22:25] offset:64256
	ds_write_b128 v214, v[6:9]
	ds_write_b128 v178, v[26:29] offset:16384
	ds_write_b128 v213, v[10:13]
	ds_write_b128 v178, v[30:33] offset:24576
	ds_write_b128 v179, v[14:17]
	s_cbranch_vccz .LBB0_943
	v_lshl_add_u32 v4, v211, 4, s27
	ds_read2_b32 v[2:3], v4 offset1:1
	ds_read2_b32 v[4:5], v4 offset0:2 offset1:3
	v_cmp_gt_u32_e32 vcc, 32, v211
	s_waitcnt lgkmcnt(1)
	ds_bpermute_b32 v6, v198, v2
	s_waitcnt lgkmcnt(0)
	v_or_b32_e32 v2, v6, v2
	ds_bpermute_b32 v6, v198, v3
	s_waitcnt lgkmcnt(0)
	v_or_b32_e32 v3, v6, v3
	ds_bpermute_b32 v6, v198, v4
	s_waitcnt lgkmcnt(0)
	v_or_b32_e32 v4, v6, v4
	ds_bpermute_b32 v6, v198, v5
	s_waitcnt lgkmcnt(0)
	v_or_b32_e32 v5, v6, v5
	ds_bpermute_b32 v6, v199, v2
	s_waitcnt lgkmcnt(0)
	v_or_b32_e32 v2, v6, v2
	ds_bpermute_b32 v6, v199, v3
	s_waitcnt lgkmcnt(0)
	v_or_b32_e32 v3, v6, v3
	ds_bpermute_b32 v6, v199, v4
	s_waitcnt lgkmcnt(0)
	v_or_b32_e32 v4, v6, v4
	ds_bpermute_b32 v6, v199, v5
	s_waitcnt lgkmcnt(0)
	v_or_b32_e32 v5, v6, v5
	ds_bpermute_b32 v6, v200, v2
	s_waitcnt lgkmcnt(0)
	v_or_b32_e32 v2, v6, v2
	ds_bpermute_b32 v6, v200, v3
	s_waitcnt lgkmcnt(0)
	v_or_b32_e32 v3, v6, v3
	ds_bpermute_b32 v6, v200, v4
	s_waitcnt lgkmcnt(0)
	v_or_b32_e32 v4, v6, v4
	ds_bpermute_b32 v6, v200, v5
	s_waitcnt lgkmcnt(0)
	v_or_b32_e32 v5, v6, v5
	ds_bpermute_b32 v6, v201, v2
	s_waitcnt lgkmcnt(0)
	v_or_b32_e32 v2, v6, v2
	ds_bpermute_b32 v6, v201, v3
	s_waitcnt lgkmcnt(0)
	v_or_b32_e32 v3, v6, v3
	ds_bpermute_b32 v6, v201, v4
	s_waitcnt lgkmcnt(0)
	v_or_b32_e32 v4, v6, v4
	ds_bpermute_b32 v6, v201, v5
	s_waitcnt lgkmcnt(0)
	v_or_b32_e32 v5, v6, v5
	ds_bpermute_b32 v6, v202, v2
	s_waitcnt lgkmcnt(0)
	v_or_b32_e32 v2, v6, v2
	ds_bpermute_b32 v6, v202, v3
	s_waitcnt lgkmcnt(0)
	v_or_b32_e32 v3, v6, v3
	ds_bpermute_b32 v6, v202, v4
	s_waitcnt lgkmcnt(0)
	v_or_b32_e32 v4, v6, v4
	ds_bpermute_b32 v6, v202, v5
	s_waitcnt lgkmcnt(0)
	v_or_b32_e32 v5, v6, v5
	ds_bpermute_b32 v6, v203, v2
	s_waitcnt lgkmcnt(0)
	v_or_b32_e32 v2, v6, v2
	ds_bpermute_b32 v6, v203, v3
	s_waitcnt lgkmcnt(0)
	v_or_b32_e32 v3, v6, v3
	ds_bpermute_b32 v6, v203, v4
	v_cndmask_b32_e32 v2, v3, v2, vcc
	s_waitcnt lgkmcnt(0)
	v_or_b32_e32 v4, v6, v4
	ds_bpermute_b32 v6, v203, v5
	s_waitcnt lgkmcnt(0)
	v_or_b32_e32 v5, v6, v5
	v_cndmask_b32_e32 v3, v5, v4, vcc
	v_lshlrev_b32_e64 v4, v212, 1
	v_and_b32_e32 v2, v2, v4
	v_cmp_ne_u32_e64 s[0:1], 0, v2
	v_and_b32_e32 v2, v3, v4
	v_lshlrev_b64 v[4:5], v211, -1
	v_cmp_ne_u32_e32 vcc, 0, v2
	v_not_b32_e32 v2, v5
	v_not_b32_e32 v3, v4
	s_and_saveexec_b64 s[2:3], s[0:1]
	s_cbranch_execz .LBB0_1010
	v_and_b32_e32 v5, s0, v3
	v_and_b32_e32 v4, s1, v2
	v_bcnt_u32_b32 v5, v5, 0
	v_bcnt_u32_b32 v4, v4, v5
	v_lshl_add_u32 v4, v4, 2, s29
	ds_write_b32 v4, v211 offset:4
	s_or_b64 exec, exec, s[2:3]
	s_bcnt1_i32_b64 s4, s[0:1]
	s_and_saveexec_b64 s[0:1], vcc
	s_cbranch_execnz .LBB0_1011
	.p2align 6
.LBB0_940:
	s_or_b64 exec, exec, s[0:1]
	v_cmp_eq_u32_e64 s[0:1], 0, v211
	s_and_saveexec_b64 s[2:3], s[0:1]
	.p2align 6
.LBB0_941:
	s_bcnt1_i32_b64 s0, vcc
	s_add_i32 s0, s0, s4
	v_mov_b32_e32 v2, s29
	v_mov_b32_e32 v3, s0
	ds_write_b32 v2, v3
	.p2align 6

.LBB0_945:
	v_mov_b32_e32 v14, v1
	v_mov_b32_e32 v15, v1
	v_mov_b32_e32 v0, v1
	v_mov_b32_e32 v2, v1
	v_mov_b32_e32 v3, v1
	v_mov_b32_e32 v4, v1
	v_mov_b32_e32 v5, v1
	v_mov_b32_e32 v6, v1
	v_mov_b32_e32 v7, v1
	v_mov_b32_e32 v8, v1
	v_mov_b32_e32 v9, v1
	v_mov_b32_e32 v10, v1
	v_mov_b32_e32 v11, v1
	v_mov_b32_e32 v12, v1
	v_mov_b32_e32 v13, v1
	v_mov_b64_e32 v[62:63], v[14:15]
	v_mov_b64_e32 v[46:47], v[14:15]
	v_mov_b32_e32 v106, 0
	v_mov_b64_e32 v[60:61], v[12:13]
	v_mov_b64_e32 v[58:59], v[10:11]
	v_mov_b64_e32 v[56:57], v[8:9]
	v_mov_b64_e32 v[54:55], v[6:7]
	v_mov_b64_e32 v[52:53], v[4:5]
	v_mov_b64_e32 v[50:51], v[2:3]
	v_mov_b64_e32 v[48:49], v[0:1]
	v_mov_b64_e32 v[44:45], v[12:13]
	v_mov_b64_e32 v[42:43], v[10:11]
	v_mov_b64_e32 v[40:41], v[8:9]
	v_mov_b64_e32 v[38:39], v[6:7]
	v_mov_b64_e32 v[36:37], v[4:5]
	v_mov_b64_e32 v[34:35], v[2:3]
	v_mov_b64_e32 v[32:33], v[0:1]
	.p2align 6

.LBB0_947:
	s_mov_b32 s0, s94
	s_andn2_b64 vcc, exec, s[2:3]
	s_cbranch_vccnz .LBB0_945
	s_lshl_b32 s1, s0, 12
	s_and_b32 s1, s1, 0xffffe000
	s_mul_hi_i32 s72, s1, 0x2640
	s_mulk_i32 s1, 0x2640
	v_readlane_b32 s76, v254, 54
	v_readlane_b32 s77, v254, 55
	s_add_u32 s1, s76, s1
	s_addc_u32 s72, s77, s72
	s_lshl_b32 s0, s0, 7
	s_and_b32 s0, s0, 0x80
	v_mov_b32_e32 v0, s92
	s_add_u32 s0, s1, s0
	ds_read_b32 v0, v0
	s_addc_u32 s1, s72, 0
	s_add_u32 s72, s0, 0x1200
	s_addc_u32 s73, s1, 0
	s_add_u32 s76, s0, 0x1300
	s_addc_u32 s77, s1, 0
	s_waitcnt lgkmcnt(0)
	v_lshl_add_u32 v6, v0, 6, v100
	v_mov_b64_e32 v[2:3], s[72:73]
	v_mad_i64_i32 v[2:3], s[0:1], v6, s90, v[2:3]
	v_lshlrev_b32_e32 v0, 1, v102
	v_mov_b64_e32 v[4:5], s[76:77]
	v_lshl_add_u64 v[2:3], v[2:3], 0, v[0:1]
	v_mad_i64_i32 v[4:5], s[0:1], v6, s90, v[4:5]
	v_lshl_add_u64 v[4:5], v[4:5], 0, v[0:1]
	global_load_dwordx4 v[26:29], v[2:3], off
	global_load_dwordx4 v[96:99], v[4:5], off
	v_cndmask_b32_e64 v2, 0, 1, s[4:5]
	v_cmp_ne_u32_e64 s[0:1], 1, v2
	s_andn2_b64 vcc, exec, s[4:5]
	s_cbranch_vccnz .LBB0_976
	v_readlane_b32 s81, v254, 37
	v_mov_b64_e32 v[4:5], s[76:77]
	s_nop 0
	v_mov_b32_e32 v2, s81
	ds_read_b32 v6, v2
	v_mov_b64_e32 v[2:3], s[72:73]
	s_waitcnt lgkmcnt(0)
	v_lshl_add_u32 v6, v6, 6, v100
	v_mad_i64_i32 v[2:3], s[82:83], v6, s90, v[2:3]
	v_lshl_add_u64 v[2:3], v[2:3], 0, v[0:1]
	v_mad_i64_i32 v[4:5], s[82:83], v6, s90, v[4:5]
	v_lshl_add_u64 v[4:5], v[4:5], 0, v[0:1]
	global_load_dwordx4 v[18:21], v[2:3], off
	global_load_dwordx4 v[22:25], v[4:5], off
	s_and_b64 vcc, exec, s[0:1]
	s_waitcnt vmcnt(3)
	ds_write_b128 v101, v[26:29]
	s_waitcnt vmcnt(2)
	ds_write_b128 v101, v[96:99] offset:9216
	s_cbranch_vccz .LBB0_977
	.p2align 6
.LBB0_950:
	s_andn2_b64 vcc, exec, s[74:75]
	s_cbranch_vccnz .LBB0_952
	.p2align 6
.LBB0_951:
	v_readlane_b32 s0, v254, 38
	v_mov_b64_e32 v[4:5], s[76:77]
	s_nop 0
	v_mov_b32_e32 v2, s0
	ds_read_b32 v6, v2
	v_mov_b64_e32 v[2:3], s[72:73]
	s_waitcnt lgkmcnt(0)
	v_lshl_add_u32 v6, v6, 6, v100
	v_mad_i64_i32 v[2:3], s[0:1], v6, s90, v[2:3]
	v_lshl_add_u64 v[2:3], v[2:3], 0, v[0:1]
	v_mad_i64_i32 v[4:5], s[0:1], v6, s90, v[4:5]
	v_lshl_add_u64 v[4:5], v[4:5], 0, v[0:1]
	global_load_dwordx4 v[26:29], v[2:3], off
	global_load_dwordx4 v[96:99], v[4:5], off
	.p2align 6

.Lsel_pre_n1:
	s_nop 1
	s_cmp_lg_u64 s[72:73], -1
	s_cbranch_scc0 .Lsel_step_0
	v_add_u32_e32 v0, s81, v208
	ds_read_b128 v[108:111], v0
	ds_read_b128 v[112:115], v0 offset:4608
	ds_read_b128 v[116:119], v0 offset:32
	ds_read_b128 v[120:123], v0 offset:4640
	s_waitcnt lgkmcnt(3)
	v_mfma_f32_32x32x16_bf16 v[80:95], v[108:111], v[128:131], v[2:17]
	ds_read_b128 v[108:111], v0 offset:64
	s_waitcnt lgkmcnt(3)
	v_mfma_f32_32x32x16_bf16 v[64:79], v[112:115], v[128:131], v[2:17]
	ds_read_b128 v[112:115], v0 offset:4672
	s_waitcnt lgkmcnt(3)
	v_mfma_f32_32x32x16_bf16 v[80:95], v[116:119], v[132:135], v[80:95]
	ds_read_b128 v[116:119], v0 offset:96
	s_waitcnt lgkmcnt(3)
	v_mfma_f32_32x32x16_bf16 v[64:79], v[120:123], v[132:135], v[64:79]
	ds_read_b128 v[120:123], v0 offset:4704
	s_waitcnt lgkmcnt(3)
	v_mfma_f32_32x32x16_bf16 v[80:95], v[108:111], v[136:139], v[80:95]
	s_waitcnt lgkmcnt(2)
	v_mfma_f32_32x32x16_bf16 v[64:79], v[112:115], v[136:139], v[64:79]
	s_waitcnt lgkmcnt(1)
	v_mfma_f32_32x32x16_bf16 v[80:95], v[116:119], v[140:143], v[80:95]
	s_waitcnt lgkmcnt(0)
	v_mfma_f32_32x32x16_bf16 v[64:79], v[120:123], v[140:143], v[64:79]
	.p2align 6

.LBB0_988:
	v_lshl_add_u64 v[174:175], s[0:1], 0, v[0:1]
	v_readlane_b32 s0, v254, 42
	s_add_i32 s85, s85, s0
	v_lshl_add_u64 v[176:177], s[2:3], 0, v[0:1]
	v_add_u32_e32 v0, s85, v209
	s_waitcnt lgkmcnt(0)
	s_barrier
	s_lshl_b32 s7, s8, 6
	v_sub_u32_e32 v0, v0, v211
	v_mov_b32_e32 v14, v1
	v_mov_b32_e32 v15, v1
	v_subrev_u32_e32 v209, s7, v0
	v_mov_b32_e32 v0, v1
	v_mov_b32_e32 v2, v1
	v_mov_b32_e32 v3, v1
	v_mov_b32_e32 v4, v1
	v_mov_b32_e32 v5, v1
	v_mov_b32_e32 v6, v1
	v_mov_b32_e32 v7, v1
	v_mov_b32_e32 v8, v1
	v_mov_b32_e32 v9, v1
	v_mov_b32_e32 v10, v1
	v_mov_b32_e32 v11, v1
	v_mov_b32_e32 v12, v1
	v_mov_b32_e32 v13, v1
	v_mov_b64_e32 v[62:63], v[14:15]
	v_mov_b64_e32 v[30:31], v[14:15]
	v_mov_b64_e32 v[46:47], v[14:15]
	s_mov_b32 s10, 4
	v_add_u32_e32 v210, 0xffffff00, v100
	s_sub_i32 s8, s8, s84
	v_sub_u32_e32 v212, v211, v205
	v_add_u32_e32 v216, 0xfffffec0, v100
	s_mov_b32 s9, 0
	v_mov_b32_e32 v96, 0
	v_mov_b64_e32 v[60:61], v[12:13]
	v_mov_b64_e32 v[58:59], v[10:11]
	v_mov_b64_e32 v[56:57], v[8:9]
	v_mov_b64_e32 v[54:55], v[6:7]
	v_mov_b64_e32 v[52:53], v[4:5]
	v_mov_b64_e32 v[50:51], v[2:3]
	v_mov_b64_e32 v[48:49], v[0:1]
	v_mov_b64_e32 v[28:29], v[12:13]
	v_mov_b64_e32 v[26:27], v[10:11]
	v_mov_b64_e32 v[24:25], v[8:9]
	v_mov_b64_e32 v[22:23], v[6:7]
	v_mov_b64_e32 v[20:21], v[4:5]
	v_mov_b64_e32 v[18:19], v[2:3]
	v_mov_b64_e32 v[16:17], v[0:1]
	v_mov_b64_e32 v[44:45], v[12:13]
	v_mov_b64_e32 v[42:43], v[10:11]
	v_mov_b64_e32 v[40:41], v[8:9]
	v_mov_b64_e32 v[38:39], v[6:7]
	v_mov_b64_e32 v[36:37], v[4:5]
	v_mov_b64_e32 v[34:35], v[2:3]
	v_mov_b64_e32 v[32:33], v[0:1]
	.p2align 6

.LBB0_1069:
	s_add_u32 s2, s6, 0xde00000
	s_addc_u32 s3, s7, 0
	s_lshl_b32 s8, s8, 5
	s_and_b32 s12, s8, 0x60
	s_add_i32 m0, s46, 0x18000
	v_lshl_add_u64 v[8:9], v[8:9], 0, s[88:89]
	s_lshl_b32 s11, s5, 13
	s_lshl_b32 s13, s12, 7
	s_waitcnt vmcnt(2)
	s_barrier
	global_load_lds_dwordx4 v[8:9], off
	v_lshl_add_u64 v[6:7], v[6:7], 0, s[88:89]
	s_add_i32 m0, s46, 0x1a000
	s_add_i32 s50, s46, 0x8000
	s_add_i32 s51, s46, 0xa000
	global_load_lds_dwordx4 v[6:7], off
	v_lshl_add_u64 v[2:3], v[2:3], 0, s[88:89]
	s_mov_b32 m0, s50
	s_add_u32 s8, s22, 0x40080
	global_load_lds_dwordx4 v[2:3], off
	v_lshl_add_u64 v[2:3], v[4:5], 0, s[88:89]
	s_mov_b32 m0, s51
	s_addc_u32 s9, s23, 0
	global_load_lds_dwordx4 v[2:3], off
	s_add_i32 m0, s46, 0x1c000
	v_lshl_add_u64 v[2:3], s[8:9], 0, v[132:133]
	global_load_lds_dwordx4 v[2:3], off
	v_lshl_add_u64 v[2:3], s[8:9], 0, v[134:135]
	s_add_i32 m0, s46, 0x1e000
	s_sext_i32_i8 s21, s4
	global_load_lds_dwordx4 v[2:3], off
	v_bfe_u32 v3, v0, 4, 2
	v_and_b32_e32 v2, 15, v0
	v_lshlrev_b32_e32 v4, 4, v3
	v_lshlrev_b32_e32 v0, 2, v0
	v_lshl_or_b32 v137, s5, 6, v2
	v_lshl_or_b32 v2, v2, 6, v4
	v_and_b32_e32 v0, 32, v0
	v_bitop3_b32 v4, v2, s11, v0 bitop3:0xde
	s_waitcnt vmcnt(0)
	v_bitop3_b32 v148, v2, s13, v0 bitop3:0xde
	v_lshlrev_b32_e32 v0, 14, v10
	v_and_b32_e32 v0, 0xffff8000, v0
	v_lshl_add_u32 v0, v11, 11, v0
	v_and_b32_e32 v2, 1, v10
	s_add_u32 s4, s6, 0x2401600
	v_lshl_or_b32 v0, v2, 6, v0
	s_addc_u32 s5, s7, 0
	v_lshl_add_u32 v138, v12, 1, v0
	v_lshlrev_b32_e32 v0, 14, v13
	s_add_u32 s8, s6, 0x2401e00
	v_and_b32_e32 v0, 0xffff8000, v0
	s_waitcnt vmcnt(6)
	s_addc_u32 s9, s7, 0
	v_lshl_add_u32 v0, v14, 11, v0
	v_and_b32_e32 v2, 1, v13
	s_cmpk_lt_u32 s10, 0x100
	v_lshl_or_b32 v0, v2, 6, v0
	v_lshl_or_b32 v136, v3, 2, s12
	v_add_u32_e32 v149, 0xb0, v137
	s_cselect_b64 s[10:11], -1, 0
	s_ashr_i32 s52, s38, 31
	v_mov_b32_e32 v139, v1
	v_lshl_add_u32 v140, v15, 1, v0
	v_mov_b32_e32 v141, v1
	s_mov_b32 s53, 0
	v_add_u32_e32 v150, 0, v4
	s_barrier
	s_branch .LBB0_1072
	.p2align 6

.LBB0_1078:
	s_ashr_i32 s15, s14, 31
	s_lshl_b64 s[16:17], s[14:15], 19
	s_add_u32 s16, s41, s16
	s_addc_u32 s17, s42, s17
	s_and_b64 s[18:19], s[6:7], exec
	s_cselect_b32 s15, s17, s25
	s_cselect_b32 s33, s16, s24
	s_ashr_i32 s13, s12, 31
	s_lshl_b64 s[18:19], s[12:13], 19
	s_add_u32 s18, s43, s18
	s_addc_u32 s19, s44, s19
	s_and_b64 s[26:27], s[6:7], exec
	s_cselect_b32 s54, s19, s23
	s_cselect_b32 s55, s18, s22
	s_lshl_b32 s20, s20, 8
	v_or_b32_e32 v0, 16, v137
	v_add_u32_e32 v152, s20, v0
	v_or_b32_e32 v0, 32, v137
	v_add_u32_e32 v153, s20, v0
	v_or_b32_e32 v0, 48, v137
	v_add_u32_e32 v154, s20, v0
	v_add_u32_e32 v0, 0x80, v137
	s_lshl_b32 s13, s21, 8
	v_add_u32_e32 v155, s20, v0
	v_add_u32_e32 v0, 0x90, v137
	s_or_b32 s56, s13, 16
	s_or_b32 s57, s13, 0x80
	s_or_b32 s58, s13, 0x90
	v_add_u32_e32 v156, s20, v0
	v_add_u32_e32 v0, 0xa0, v137
	v_add_u32_e32 v151, s20, v137
	v_add_u32_e32 v157, s20, v0
	v_add_u32_e32 v158, s20, v149
	s_add_u32 s20, s24, 0x100
	s_addc_u32 s21, s25, 0
	s_add_u32 s22, s22, 0x100
	s_addc_u32 s23, s23, 0
	s_add_u32 s24, s24, 0x40080
	v_mov_b32_e32 v2, v1
	v_mov_b32_e32 v3, v1
	s_addc_u32 s25, s25, 0
	v_mov_b32_e32 v0, v1
	v_mov_b64_e32 v[6:7], v[2:3]
	v_mov_b64_e32 v[10:11], v[2:3]
	v_mov_b64_e32 v[22:23], v[2:3]
	v_mov_b64_e32 v[26:27], v[2:3]
	v_mov_b64_e32 v[38:39], v[2:3]
	v_mov_b64_e32 v[42:43], v[2:3]
	v_mov_b64_e32 v[54:55], v[2:3]
	v_mov_b64_e32 v[58:59], v[2:3]
	v_mov_b64_e32 v[14:15], v[2:3]
	v_mov_b64_e32 v[18:19], v[2:3]
	v_mov_b64_e32 v[30:31], v[2:3]
	v_mov_b64_e32 v[34:35], v[2:3]
	v_mov_b64_e32 v[46:47], v[2:3]
	v_mov_b64_e32 v[50:51], v[2:3]
	v_mov_b64_e32 v[62:63], v[2:3]
	v_mov_b64_e32 v[66:67], v[2:3]
	v_mov_b64_e32 v[70:71], v[2:3]
	v_mov_b64_e32 v[74:75], v[2:3]
	v_mov_b64_e32 v[86:87], v[2:3]
	v_mov_b64_e32 v[90:91], v[2:3]
	v_mov_b64_e32 v[102:103], v[2:3]
	v_mov_b64_e32 v[106:107], v[2:3]
	v_mov_b64_e32 v[118:119], v[2:3]
	v_mov_b64_e32 v[122:123], v[2:3]
	v_mov_b64_e32 v[78:79], v[2:3]
	v_mov_b64_e32 v[82:83], v[2:3]
	v_mov_b64_e32 v[94:95], v[2:3]
	v_mov_b64_e32 v[98:99], v[2:3]
	v_mov_b64_e32 v[110:111], v[2:3]
	v_mov_b64_e32 v[114:115], v[2:3]
	v_mov_b64_e32 v[126:127], v[2:3]
	v_mov_b64_e32 v[130:131], v[2:3]
	v_lshl_add_u64 v[142:143], s[24:25], 0, v[138:139]
	v_lshl_add_u64 v[144:145], s[24:25], 0, v[140:141]
	s_mov_b64 s[24:25], -1
	s_mov_b64 s[26:27], 0
	v_mov_b64_e32 v[4:5], v[0:1]
	v_mov_b64_e32 v[8:9], v[0:1]
	v_mov_b64_e32 v[20:21], v[0:1]
	v_mov_b64_e32 v[24:25], v[0:1]
	v_mov_b64_e32 v[36:37], v[0:1]
	v_mov_b64_e32 v[40:41], v[0:1]
	v_mov_b64_e32 v[52:53], v[0:1]
	v_mov_b64_e32 v[56:57], v[0:1]
	v_mov_b64_e32 v[12:13], v[0:1]
	v_mov_b64_e32 v[16:17], v[0:1]
	v_mov_b64_e32 v[28:29], v[0:1]
	v_mov_b64_e32 v[32:33], v[0:1]
	v_mov_b64_e32 v[44:45], v[0:1]
	v_mov_b64_e32 v[48:49], v[0:1]
	v_mov_b64_e32 v[60:61], v[0:1]
	v_mov_b64_e32 v[64:65], v[0:1]
	v_mov_b64_e32 v[68:69], v[0:1]
	v_mov_b64_e32 v[72:73], v[0:1]
	v_mov_b64_e32 v[84:85], v[0:1]
	v_mov_b64_e32 v[88:89], v[0:1]
	v_mov_b64_e32 v[100:101], v[0:1]
	v_mov_b64_e32 v[104:105], v[0:1]
	v_mov_b64_e32 v[116:117], v[0:1]
	v_mov_b64_e32 v[120:121], v[0:1]
	v_mov_b64_e32 v[76:77], v[0:1]
	v_mov_b64_e32 v[80:81], v[0:1]
	v_mov_b64_e32 v[92:93], v[0:1]
	v_mov_b64_e32 v[96:97], v[0:1]
	v_mov_b64_e32 v[108:109], v[0:1]
	v_mov_b64_e32 v[112:113], v[0:1]
	v_mov_b64_e32 v[124:125], v[0:1]
	v_mov_b64_e32 v[128:129], v[0:1]
	s_branch .LBB0_1080
	.p2align 6

.LBB0_1082:
	s_and_b64 s[26:27], s[26:27], exec
	s_cselect_b32 s59, 8, 0
	s_and_b64 s[26:27], s[24:25], exec
	s_cselect_b32 s60, 8, 16
	s_cmp_ge_u32 s59, s60
	s_mov_b64 s[70:71], 0x100
	s_cbranch_scc1 .LBB0_1079
	s_lshl_b32 s80, s59, 7
	s_mov_b64 s[26:27], 0x700
	v_mov_b64_e32 v[2:3], v[144:145]
	v_mov_b64_e32 v[146:147], v[142:143]
	s_mov_b64 s[28:29], s[22:23]
	s_mov_b64 s[30:31], s[20:21]
	.p2align 6

.LBB0_1144:
	s_add_u32 s12, s2, 0xbe00000
	s_addc_u32 s13, s3, 0
	s_and_b32 s48, s6, 3
	s_add_i32 m0, s44, 0x18000
	v_lshl_add_u64 v[8:9], v[8:9], 0, s[88:89]
	s_lshl_b32 s6, s7, 13
	s_lshl_b32 s15, s48, 12
	s_waitcnt vmcnt(2)
	s_barrier
	global_load_lds_dwordx4 v[8:9], off
	v_lshl_add_u64 v[6:7], v[6:7], 0, s[88:89]
	s_add_i32 m0, s44, 0x1a000
	s_add_i32 s49, s44, 0x8000
	s_add_i32 s50, s44, 0xa000
	global_load_lds_dwordx4 v[6:7], off
	v_lshl_add_u64 v[2:3], v[2:3], 0, s[88:89]
	s_mov_b32 m0, s49
	s_add_u32 s8, s30, 0x40080
	global_load_lds_dwordx4 v[2:3], off
	v_lshl_add_u64 v[2:3], v[4:5], 0, s[88:89]
	s_mov_b32 m0, s50
	s_addc_u32 s9, s31, 0
	global_load_lds_dwordx4 v[2:3], off
	s_add_i32 m0, s44, 0x1c000
	v_lshl_add_u64 v[2:3], s[8:9], 0, v[0:1]
	global_load_lds_dwordx4 v[2:3], off
	v_lshl_add_u64 v[2:3], s[8:9], 0, v[130:131]
	s_add_i32 m0, s44, 0x1e000
	s_mov_b64 s[8:9], 0x40080
	global_load_lds_dwordx4 v[2:3], off
	v_bfe_u32 v2, v10, 4, 2
	v_and_b32_e32 v3, 15, v10
	v_lshlrev_b32_e32 v4, 4, v2
	s_waitcnt vmcnt(0)
	v_lshl_or_b32 v148, s7, 6, v3
	v_lshl_or_b32 v3, v3, 6, v4
	v_lshlrev_b32_e32 v4, 2, v10
	v_and_b32_e32 v4, 32, v4
	v_bitop3_b32 v5, v3, s6, v4 bitop3:0xde
	v_bitop3_b32 v149, v3, s15, v4 bitop3:0xde
	v_lshlrev_b32_e32 v3, 2, v2
	v_cmp_eq_u32_e64 s[6:7], 0, v2
	v_lshlrev_b32_e32 v2, 13, v11
	v_and_b32_e32 v2, 0x7fffc000, v2
	v_lshl_add_u32 v2, v12, 10, v2
	v_or_b32_e32 v2, v2, v13
	v_lshl_or_b32 v150, s48, 5, v3
	v_add_lshl_u32 v2, v2, v14, 1
	v_mov_b32_e32 v3, v1
	v_lshl_add_u64 v[132:133], v[2:3], 0, s[8:9]
	v_lshlrev_b32_e32 v2, 13, v15
	v_and_b32_e32 v2, 0x7fffc000, v2
	v_lshl_add_u32 v2, v16, 10, v2
	s_waitcnt vmcnt(6)
	v_or_b32_e32 v2, v2, v17
	s_cmpk_lt_u32 s14, 0x100
	v_add_lshl_u32 v2, v2, v18, 1
	s_cselect_b64 s[14:15], -1, 0
	s_mov_b32 s51, 0
	s_ashr_i32 s52, s33, 31
	s_ashr_i32 s53, s38, 31
	v_lshl_add_u64 v[134:135], v[2:3], 0, s[8:9]
	v_add_u32_e32 v151, 0, v5
	s_barrier
	s_branch .LBB0_1147
	.p2align 6
.LBB0_1145:
	s_mov_b64 s[8:9], 0
	.p2align 6

.LBB0_1153:
	s_ashr_i32 s19, s18, 31
	s_lshl_b64 s[20:21], s[18:19], 19
	s_add_u32 s20, s39, s20
	s_addc_u32 s21, s40, s21
	s_and_b64 s[22:23], s[8:9], exec
	s_cselect_b32 s19, s21, s29
	s_cselect_b32 s25, s20, s28
	s_ashr_i32 s17, s16, 31
	s_lshl_b64 s[22:23], s[16:17], 19
	s_add_u32 s22, s41, s22
	s_addc_u32 s23, s42, s23
	s_and_b64 s[34:35], s[8:9], exec
	s_cselect_b32 s17, s23, s31
	s_cselect_b32 s27, s22, s30
	s_add_u32 s54, s30, 0x100
	v_mov_b32_e32 v2, 0
	s_addc_u32 s55, s31, 0
	s_mov_b32 s56, -2
	v_mov_b32_e32 v3, v2
	v_mov_b32_e32 v4, v2
	v_mov_b32_e32 v5, v2
	v_mov_b32_e32 v6, v2
	v_mov_b32_e32 v7, v2
	v_mov_b32_e32 v8, v2
	v_mov_b32_e32 v9, v2
	v_mov_b32_e32 v18, v2
	v_mov_b32_e32 v19, v2
	v_mov_b32_e32 v20, v2
	v_mov_b32_e32 v21, v2
	v_mov_b32_e32 v22, v2
	v_mov_b32_e32 v23, v2
	v_mov_b32_e32 v24, v2
	v_mov_b32_e32 v25, v2
	v_mov_b32_e32 v34, v2
	v_mov_b32_e32 v35, v2
	v_mov_b32_e32 v36, v2
	v_mov_b32_e32 v37, v2
	v_mov_b32_e32 v38, v2
	v_mov_b32_e32 v39, v2
	v_mov_b32_e32 v40, v2
	v_mov_b32_e32 v41, v2
	v_mov_b32_e32 v50, v2
	v_mov_b32_e32 v51, v2
	v_mov_b32_e32 v52, v2
	v_mov_b32_e32 v53, v2
	v_mov_b32_e32 v54, v2
	v_mov_b32_e32 v55, v2
	v_mov_b32_e32 v56, v2
	v_mov_b32_e32 v57, v2
	v_mov_b32_e32 v10, v2
	v_mov_b32_e32 v11, v2
	v_mov_b32_e32 v12, v2
	v_mov_b32_e32 v13, v2
	v_mov_b32_e32 v14, v2
	v_mov_b32_e32 v15, v2
	v_mov_b32_e32 v16, v2
	v_mov_b32_e32 v17, v2
	v_mov_b32_e32 v26, v2
	v_mov_b32_e32 v27, v2
	v_mov_b32_e32 v28, v2
	v_mov_b32_e32 v29, v2
	v_mov_b32_e32 v30, v2
	v_mov_b32_e32 v31, v2
	v_mov_b32_e32 v32, v2
	v_mov_b32_e32 v33, v2
	v_mov_b32_e32 v42, v2
	v_mov_b32_e32 v43, v2
	v_mov_b32_e32 v44, v2
	v_mov_b32_e32 v45, v2
	v_mov_b32_e32 v46, v2
	v_mov_b32_e32 v47, v2
	v_mov_b32_e32 v48, v2
	v_mov_b32_e32 v49, v2
	v_mov_b32_e32 v58, v2
	v_mov_b32_e32 v59, v2
	v_mov_b32_e32 v60, v2
	v_mov_b32_e32 v61, v2
	v_mov_b32_e32 v62, v2
	v_mov_b32_e32 v63, v2
	v_mov_b32_e32 v64, v2
	v_mov_b32_e32 v65, v2
	v_mov_b32_e32 v66, v2
	v_mov_b32_e32 v67, v2
	v_mov_b32_e32 v68, v2
	v_mov_b32_e32 v69, v2
	v_mov_b32_e32 v70, v2
	v_mov_b32_e32 v71, v2
	v_mov_b32_e32 v72, v2
	v_mov_b32_e32 v73, v2
	v_mov_b32_e32 v82, v2
	v_mov_b32_e32 v83, v2
	v_mov_b32_e32 v84, v2
	v_mov_b32_e32 v85, v2
	v_mov_b32_e32 v86, v2
	v_mov_b32_e32 v87, v2
	v_mov_b32_e32 v88, v2
	v_mov_b32_e32 v89, v2
	v_mov_b32_e32 v98, v2
	v_mov_b32_e32 v99, v2
	v_mov_b32_e32 v100, v2
	v_mov_b32_e32 v101, v2
	v_mov_b32_e32 v102, v2
	v_mov_b32_e32 v103, v2
	v_mov_b32_e32 v104, v2
	v_mov_b32_e32 v105, v2
	v_mov_b32_e32 v114, v2
	v_mov_b32_e32 v115, v2
	v_mov_b32_e32 v116, v2
	v_mov_b32_e32 v117, v2
	v_mov_b32_e32 v118, v2
	v_mov_b32_e32 v119, v2
	v_mov_b32_e32 v120, v2
	v_mov_b32_e32 v121, v2
	v_mov_b32_e32 v74, v2
	v_mov_b32_e32 v75, v2
	v_mov_b32_e32 v76, v2
	v_mov_b32_e32 v77, v2
	v_mov_b32_e32 v78, v2
	v_mov_b32_e32 v79, v2
	v_mov_b32_e32 v80, v2
	v_mov_b32_e32 v81, v2
	v_mov_b32_e32 v90, v2
	v_mov_b32_e32 v91, v2
	v_mov_b32_e32 v92, v2
	v_mov_b32_e32 v93, v2
	v_mov_b32_e32 v94, v2
	v_mov_b32_e32 v95, v2
	v_mov_b32_e32 v96, v2
	v_mov_b32_e32 v97, v2
	v_mov_b32_e32 v106, v2
	v_mov_b32_e32 v107, v2
	v_mov_b32_e32 v108, v2
	v_mov_b32_e32 v109, v2
	v_mov_b32_e32 v110, v2
	v_mov_b32_e32 v111, v2
	v_mov_b32_e32 v112, v2
	v_mov_b32_e32 v113, v2
	v_mov_b32_e32 v122, v2
	v_mov_b32_e32 v123, v2
	v_mov_b32_e32 v124, v2
	v_mov_b32_e32 v125, v2
	v_mov_b32_e32 v126, v2
	v_mov_b32_e32 v127, v2
	v_mov_b32_e32 v128, v2
	v_mov_b32_e32 v129, v2
	.p2align 6

.LBB0_1230:
	s_add_u32 s10, s2, 0x2400000
	s_addc_u32 s11, s3, 0
	s_lshl_b32 s9, s12, 5
	s_and_b32 s9, s9, 0x60
	s_add_i32 m0, s36, 0x18000
	v_lshl_add_u64 v[8:9], v[8:9], 0, s[88:89]
	s_lshl_b32 s1, s7, 13
	s_lshl_b32 s14, s9, 7
	s_waitcnt vmcnt(2)
	s_barrier
	global_load_lds_dwordx4 v[8:9], off
	v_lshl_add_u64 v[6:7], v[6:7], 0, s[88:89]
	s_add_i32 m0, s36, 0x1a000
	s_add_i32 s40, s36, 0x8000
	s_add_i32 s41, s36, 0xa000
	global_load_lds_dwordx4 v[6:7], off
	v_lshl_add_u64 v[2:3], v[2:3], 0, s[88:89]
	s_mov_b32 m0, s40
	s_add_u32 s12, s24, 0x40080
	global_load_lds_dwordx4 v[2:3], off
	v_lshl_add_u64 v[2:3], v[4:5], 0, s[88:89]
	s_mov_b32 m0, s41
	s_addc_u32 s13, s25, 0
	global_load_lds_dwordx4 v[2:3], off
	s_add_i32 m0, s36, 0x1c000
	v_lshl_add_u64 v[2:3], s[12:13], 0, v[0:1]
	global_load_lds_dwordx4 v[2:3], off
	v_lshl_add_u64 v[2:3], s[12:13], 0, v[134:135]
	s_add_i32 m0, s36, 0x1e000
	s_cmpk_lt_u32 s6, 0x100
	global_load_lds_dwordx4 v[2:3], off
	v_lshrrev_b32_e32 v3, 1, v10
	v_and_b32_e32 v3, 24, v3
	v_and_b32_e32 v2, 15, v10
	v_lshlrev_b32_e32 v4, 1, v3
	s_waitcnt vmcnt(0)
	v_lshl_or_b32 v146, s7, 6, v2
	v_lshl_or_b32 v2, v2, 6, v4
	v_lshlrev_b32_e32 v4, 2, v10
	v_and_b32_e32 v4, 32, v4
	v_bitop3_b32 v5, v2, s1, v4 bitop3:0xde
	v_bitop3_b32 v147, v2, s14, v4 bitop3:0xde
	v_lshlrev_b32_e32 v2, 14, v11
	v_and_b32_e32 v2, 0xffff8000, v2
	v_or_b32_e32 v148, s9, v3
	v_lshl_add_u32 v2, v12, 11, v2
	v_and_b32_e32 v3, 1, v11
	v_lshl_or_b32 v2, v3, 6, v2
	v_lshl_add_u32 v136, v13, 1, v2
	v_lshlrev_b32_e32 v2, 14, v14
	v_and_b32_e32 v2, 0xffff8000, v2
	s_waitcnt vmcnt(6)
	v_lshl_add_u32 v2, v15, 11, v2
	v_and_b32_e32 v3, 1, v14
	v_lshl_or_b32 v2, v3, 6, v2
	s_cselect_b64 s[12:13], -1, 0
	s_ashr_i32 s42, s28, 31
	s_ashr_i32 s43, s29, 31
	v_mov_b32_e32 v137, v1
	v_lshl_add_u32 v138, v16, 1, v2
	v_mov_b32_e32 v139, v1
	s_mov_b32 s44, 0
	v_add_u32_e32 v149, 0, v5
	s_barrier
	s_branch .LBB0_1233
	.p2align 6
.LBB0_1231:
	s_mov_b64 s[0:1], 0
	.p2align 6

.LBB0_1239:
	s_ashr_i32 s17, s16, 31
	s_lshl_b64 s[18:19], s[16:17], 19
	s_add_u32 s18, s30, s18
	s_addc_u32 s19, s31, s19
	s_and_b64 s[20:21], s[6:7], exec
	s_cselect_b32 s1, s19, s23
	s_cselect_b32 s9, s18, s22
	s_ashr_i32 s15, s14, 31
	s_lshl_b64 s[20:21], s[14:15], 19
	s_add_u32 s20, s33, s20
	s_addc_u32 s21, s34, s21
	s_and_b64 s[26:27], s[6:7], exec
	s_cselect_b32 s15, s21, s25
	s_cselect_b32 s17, s20, s24
	s_add_u32 s22, s22, 0x40080
	s_addc_u32 s23, s23, 0
	s_add_u32 s45, s24, 0x100
	v_mov_b32_e32 v2, 0
	s_addc_u32 s46, s25, 0
	s_mov_b32 s47, -2
	v_mov_b32_e32 v3, v2
	v_mov_b32_e32 v4, v2
	v_mov_b32_e32 v5, v2
	v_mov_b32_e32 v6, v2
	v_mov_b32_e32 v7, v2
	v_mov_b32_e32 v8, v2
	v_mov_b32_e32 v9, v2
	v_mov_b32_e32 v18, v2
	v_mov_b32_e32 v19, v2
	v_mov_b32_e32 v20, v2
	v_mov_b32_e32 v21, v2
	v_mov_b32_e32 v22, v2
	v_mov_b32_e32 v23, v2
	v_mov_b32_e32 v24, v2
	v_mov_b32_e32 v25, v2
	v_mov_b32_e32 v34, v2
	v_mov_b32_e32 v35, v2
	v_mov_b32_e32 v36, v2
	v_mov_b32_e32 v37, v2
	v_mov_b32_e32 v38, v2
	v_mov_b32_e32 v39, v2
	v_mov_b32_e32 v40, v2
	v_mov_b32_e32 v41, v2
	v_mov_b32_e32 v50, v2
	v_mov_b32_e32 v51, v2
	v_mov_b32_e32 v52, v2
	v_mov_b32_e32 v53, v2
	v_mov_b32_e32 v54, v2
	v_mov_b32_e32 v55, v2
	v_mov_b32_e32 v56, v2
	v_mov_b32_e32 v57, v2
	v_mov_b32_e32 v10, v2
	v_mov_b32_e32 v11, v2
	v_mov_b32_e32 v12, v2
	v_mov_b32_e32 v13, v2
	v_mov_b32_e32 v14, v2
	v_mov_b32_e32 v15, v2
	v_mov_b32_e32 v16, v2
	v_mov_b32_e32 v17, v2
	v_mov_b32_e32 v26, v2
	v_mov_b32_e32 v27, v2
	v_mov_b32_e32 v28, v2
	v_mov_b32_e32 v29, v2
	v_mov_b32_e32 v30, v2
	v_mov_b32_e32 v31, v2
	v_mov_b32_e32 v32, v2
	v_mov_b32_e32 v33, v2
	v_mov_b32_e32 v42, v2
	v_mov_b32_e32 v43, v2
	v_mov_b32_e32 v44, v2
	v_mov_b32_e32 v45, v2
	v_mov_b32_e32 v46, v2
	v_mov_b32_e32 v47, v2
	v_mov_b32_e32 v48, v2
	v_mov_b32_e32 v49, v2
	v_mov_b32_e32 v58, v2
	v_mov_b32_e32 v59, v2
	v_mov_b32_e32 v60, v2
	v_mov_b32_e32 v61, v2
	v_mov_b32_e32 v62, v2
	v_mov_b32_e32 v63, v2
	v_mov_b32_e32 v64, v2
	v_mov_b32_e32 v65, v2
	v_mov_b32_e32 v66, v2
	v_mov_b32_e32 v67, v2
	v_mov_b32_e32 v68, v2
	v_mov_b32_e32 v69, v2
	v_mov_b32_e32 v70, v2
	v_mov_b32_e32 v71, v2
	v_mov_b32_e32 v72, v2
	v_mov_b32_e32 v73, v2
	v_mov_b32_e32 v82, v2
	v_mov_b32_e32 v83, v2
	v_mov_b32_e32 v84, v2
	v_mov_b32_e32 v85, v2
	v_mov_b32_e32 v86, v2
	v_mov_b32_e32 v87, v2
	v_mov_b32_e32 v88, v2
	v_mov_b32_e32 v89, v2
	v_mov_b32_e32 v98, v2
	v_mov_b32_e32 v99, v2
	v_mov_b32_e32 v100, v2
	v_mov_b32_e32 v101, v2
	v_mov_b32_e32 v102, v2
	v_mov_b32_e32 v103, v2
	v_mov_b32_e32 v104, v2
	v_mov_b32_e32 v105, v2
	v_mov_b32_e32 v114, v2
	v_mov_b32_e32 v115, v2
	v_mov_b32_e32 v116, v2
	v_mov_b32_e32 v117, v2
	v_mov_b32_e32 v118, v2
	v_mov_b32_e32 v119, v2
	v_mov_b32_e32 v120, v2
	v_mov_b32_e32 v121, v2
	v_mov_b32_e32 v74, v2
	v_mov_b32_e32 v75, v2
	v_mov_b32_e32 v76, v2
	v_mov_b32_e32 v77, v2
	v_mov_b32_e32 v78, v2
	v_mov_b32_e32 v79, v2
	v_mov_b32_e32 v80, v2
	v_mov_b32_e32 v81, v2
	v_mov_b32_e32 v90, v2
	v_mov_b32_e32 v91, v2
	v_mov_b32_e32 v92, v2
	v_mov_b32_e32 v93, v2
	v_mov_b32_e32 v94, v2
	v_mov_b32_e32 v95, v2
	v_mov_b32_e32 v96, v2
	v_mov_b32_e32 v97, v2
	v_mov_b32_e32 v106, v2
	v_mov_b32_e32 v107, v2
	v_mov_b32_e32 v108, v2
	v_mov_b32_e32 v109, v2
	v_mov_b32_e32 v110, v2
	v_mov_b32_e32 v111, v2
	v_mov_b32_e32 v112, v2
	v_mov_b32_e32 v113, v2
	v_mov_b32_e32 v122, v2
	v_mov_b32_e32 v123, v2
	v_mov_b32_e32 v124, v2
	v_mov_b32_e32 v125, v2
	v_mov_b32_e32 v126, v2
	v_mov_b32_e32 v127, v2
	v_mov_b32_e32 v128, v2
	v_mov_b32_e32 v129, v2
	.p2align 6

.LBB0_1332:
	s_add_u32 s12, s2, 0xbe00000
	s_addc_u32 s13, s3, 0
	v_readlane_b32 s14, v254, 17
	v_readlane_b32 s15, v254, 18
	s_bitcmp1_b32 s14, 0
	s_cselect_b64 s[14:15], -1, 0
	s_and_b32 s48, s6, 3
	s_add_i32 m0, s44, 0x18000
	v_lshl_add_u64 v[8:9], v[8:9], 0, s[88:89]
	s_xor_b64 s[14:15], s[14:15], -1
	s_lshl_b32 s6, s7, 13
	s_lshl_b32 s9, s48, 12
	s_waitcnt vmcnt(2)
	s_barrier
	global_load_lds_dwordx4 v[8:9], off
	v_lshl_add_u64 v[6:7], v[6:7], 0, s[88:89]
	s_add_i32 m0, s44, 0x1a000
	s_add_i32 s49, s44, 0x8000
	s_add_i32 s50, s44, 0xa000
	global_load_lds_dwordx4 v[6:7], off
	v_lshl_add_u64 v[2:3], v[2:3], 0, s[88:89]
	s_mov_b32 m0, s49
	s_add_u32 s16, s30, 0x100080
	global_load_lds_dwordx4 v[2:3], off
	v_lshl_add_u64 v[2:3], v[4:5], 0, s[88:89]
	s_mov_b32 m0, s50
	s_addc_u32 s17, s31, 0
	global_load_lds_dwordx4 v[2:3], off
	s_add_i32 m0, s44, 0x1c000
	v_lshl_add_u64 v[2:3], s[16:17], 0, v[0:1]
	global_load_lds_dwordx4 v[2:3], off
	v_lshl_add_u64 v[2:3], s[16:17], 0, v[130:131]
	s_add_i32 m0, s44, 0x1e000
	s_cmpk_lt_u32 s8, 0x100
	global_load_lds_dwordx4 v[2:3], off
	v_bfe_u32 v2, v10, 4, 2
	v_and_b32_e32 v3, 15, v10
	v_lshlrev_b32_e32 v4, 4, v2
	s_waitcnt vmcnt(0)
	v_lshl_or_b32 v150, s7, 6, v3
	v_lshl_or_b32 v3, v3, 6, v4
	v_lshlrev_b32_e32 v4, 2, v10
	v_and_b32_e32 v4, 32, v4
	v_bitop3_b32 v5, v3, s6, v4 bitop3:0xde
	v_bitop3_b32 v151, v3, s9, v4 bitop3:0xde
	v_lshlrev_b32_e32 v3, 2, v2
	v_cmp_eq_u32_e64 s[6:7], 0, v2
	v_lshlrev_b32_e32 v2, 15, v11
	v_and_b32_e32 v2, 0x7fff0000, v2
	v_lshl_add_u32 v2, v12, 12, v2
	v_or_b32_e32 v2, v2, v13
	v_lshl_or_b32 v152, s48, 5, v3
	v_add_lshl_u32 v2, v2, v14, 1
	v_mov_b32_e32 v3, v1
	s_mov_b64 s[8:9], 0x100080
	v_lshl_add_u64 v[132:133], v[2:3], 0, s[8:9]
	v_lshlrev_b32_e32 v2, 15, v15
	v_and_b32_e32 v2, 0x7fff0000, v2
	v_lshl_add_u32 v2, v16, 12, v2
	s_waitcnt vmcnt(6)
	v_or_b32_e32 v2, v2, v17
	v_add_lshl_u32 v2, v2, v18, 1
	s_cselect_b64 s[16:17], -1, 0
	s_mov_b32 s51, 0
	s_ashr_i32 s52, s33, 31
	s_ashr_i32 s53, s38, 31
	v_lshl_add_u64 v[134:135], v[2:3], 0, s[8:9]
	v_add_u32_e32 v153, 0, v5
	s_barrier
	s_branch .LBB0_1335
	.p2align 6

.LBB0_1341:
	s_ashr_i32 s21, s20, 31
	s_lshl_b64 s[22:23], s[20:21], 21
	s_add_u32 s22, s39, s22
	s_addc_u32 s23, s40, s23
	s_and_b64 s[24:25], s[8:9], exec
	s_cselect_b32 s11, s23, s29
	s_cselect_b32 s21, s22, s28
	s_ashr_i32 s19, s18, 31
	s_lshl_b64 s[24:25], s[18:19], 21
	s_add_u32 s24, s41, s24
	s_addc_u32 s25, s42, s25
	s_and_b64 s[34:35], s[8:9], exec
	s_cselect_b32 s19, s25, s31
	s_cselect_b32 s27, s24, s30
	s_add_u32 s54, s30, 0x100
	v_mov_b32_e32 v2, 0
	s_addc_u32 s55, s31, 0
	s_mov_b32 s56, -2
	v_mov_b32_e32 v3, v2
	v_mov_b32_e32 v4, v2
	v_mov_b32_e32 v5, v2
	v_mov_b32_e32 v6, v2
	v_mov_b32_e32 v7, v2
	v_mov_b32_e32 v8, v2
	v_mov_b32_e32 v9, v2
	v_mov_b32_e32 v18, v2
	v_mov_b32_e32 v19, v2
	v_mov_b32_e32 v20, v2
	v_mov_b32_e32 v21, v2
	v_mov_b32_e32 v22, v2
	v_mov_b32_e32 v23, v2
	v_mov_b32_e32 v24, v2
	v_mov_b32_e32 v25, v2
	v_mov_b32_e32 v34, v2
	v_mov_b32_e32 v35, v2
	v_mov_b32_e32 v36, v2
	v_mov_b32_e32 v37, v2
	v_mov_b32_e32 v38, v2
	v_mov_b32_e32 v39, v2
	v_mov_b32_e32 v40, v2
	v_mov_b32_e32 v41, v2
	v_mov_b32_e32 v50, v2
	v_mov_b32_e32 v51, v2
	v_mov_b32_e32 v52, v2
	v_mov_b32_e32 v53, v2
	v_mov_b32_e32 v54, v2
	v_mov_b32_e32 v55, v2
	v_mov_b32_e32 v56, v2
	v_mov_b32_e32 v57, v2
	v_mov_b32_e32 v10, v2
	v_mov_b32_e32 v11, v2
	v_mov_b32_e32 v12, v2
	v_mov_b32_e32 v13, v2
	v_mov_b32_e32 v14, v2
	v_mov_b32_e32 v15, v2
	v_mov_b32_e32 v16, v2
	v_mov_b32_e32 v17, v2
	v_mov_b32_e32 v26, v2
	v_mov_b32_e32 v27, v2
	v_mov_b32_e32 v28, v2
	v_mov_b32_e32 v29, v2
	v_mov_b32_e32 v30, v2
	v_mov_b32_e32 v31, v2
	v_mov_b32_e32 v32, v2
	v_mov_b32_e32 v33, v2
	v_mov_b32_e32 v42, v2
	v_mov_b32_e32 v43, v2
	v_mov_b32_e32 v44, v2
	v_mov_b32_e32 v45, v2
	v_mov_b32_e32 v46, v2
	v_mov_b32_e32 v47, v2
	v_mov_b32_e32 v48, v2
	v_mov_b32_e32 v49, v2
	v_mov_b32_e32 v58, v2
	v_mov_b32_e32 v59, v2
	v_mov_b32_e32 v60, v2
	v_mov_b32_e32 v61, v2
	v_mov_b32_e32 v62, v2
	v_mov_b32_e32 v63, v2
	v_mov_b32_e32 v64, v2
	v_mov_b32_e32 v65, v2
	v_mov_b32_e32 v66, v2
	v_mov_b32_e32 v67, v2
	v_mov_b32_e32 v68, v2
	v_mov_b32_e32 v69, v2
	v_mov_b32_e32 v70, v2
	v_mov_b32_e32 v71, v2
	v_mov_b32_e32 v72, v2
	v_mov_b32_e32 v73, v2
	v_mov_b32_e32 v82, v2
	v_mov_b32_e32 v83, v2
	v_mov_b32_e32 v84, v2
	v_mov_b32_e32 v85, v2
	v_mov_b32_e32 v86, v2
	v_mov_b32_e32 v87, v2
	v_mov_b32_e32 v88, v2
	v_mov_b32_e32 v89, v2
	v_mov_b32_e32 v98, v2
	v_mov_b32_e32 v99, v2
	v_mov_b32_e32 v100, v2
	v_mov_b32_e32 v101, v2
	v_mov_b32_e32 v102, v2
	v_mov_b32_e32 v103, v2
	v_mov_b32_e32 v104, v2
	v_mov_b32_e32 v105, v2
	v_mov_b32_e32 v114, v2
	v_mov_b32_e32 v115, v2
	v_mov_b32_e32 v116, v2
	v_mov_b32_e32 v117, v2
	v_mov_b32_e32 v118, v2
	v_mov_b32_e32 v119, v2
	v_mov_b32_e32 v120, v2
	v_mov_b32_e32 v121, v2
	v_mov_b32_e32 v74, v2
	v_mov_b32_e32 v75, v2
	v_mov_b32_e32 v76, v2
	v_mov_b32_e32 v77, v2
	v_mov_b32_e32 v78, v2
	v_mov_b32_e32 v79, v2
	v_mov_b32_e32 v80, v2
	v_mov_b32_e32 v81, v2
	v_mov_b32_e32 v90, v2
	v_mov_b32_e32 v91, v2
	v_mov_b32_e32 v92, v2
	v_mov_b32_e32 v93, v2
	v_mov_b32_e32 v94, v2
	v_mov_b32_e32 v95, v2
	v_mov_b32_e32 v96, v2
	v_mov_b32_e32 v97, v2
	v_mov_b32_e32 v106, v2
	v_mov_b32_e32 v107, v2
	v_mov_b32_e32 v108, v2
	v_mov_b32_e32 v109, v2
	v_mov_b32_e32 v110, v2
	v_mov_b32_e32 v111, v2
	v_mov_b32_e32 v112, v2
	v_mov_b32_e32 v113, v2
	v_mov_b32_e32 v122, v2
	v_mov_b32_e32 v123, v2
	v_mov_b32_e32 v124, v2
	v_mov_b32_e32 v125, v2
	v_mov_b32_e32 v126, v2
	v_mov_b32_e32 v127, v2
	v_mov_b32_e32 v128, v2
	v_mov_b32_e32 v129, v2
	.p2align 6

.LBB0_1472:
	v_readlane_b32 s2, v254, 0
	s_lshl_b32 s2, s2, 3
	v_readfirstlane_b32 s1, v180
	s_ashr_i32 s1, s1, 6
	s_add_i32 s2, s1, s2
	s_mov_b32 s0, 0
	s_cmpk_lt_i32 s2, 0x4000
	s_cbranch_scc0 .LBB0_1481
	s_load_dwordx4 s[8:11], s[66:67], 0x78
	s_load_dwordx2 s[4:5], s[66:67], 0x88
	v_and_b32_e32 v0, 63, v180
	v_lshlrev_b32_e32 v96, 4, v0
	v_mov_b32_e32 v97, 0
	s_waitcnt lgkmcnt(0)
	global_load_dwordx4 v[0:3], v96, s[8:9]
	global_load_dwordx4 v[4:7], v96, s[8:9] offset:1024
	global_load_dwordx4 v[8:11], v96, s[8:9] offset:2048
	global_load_dwordx4 v[12:15], v96, s[8:9] offset:3072
	s_lshl_b32 s7, s64, 3
	v_lshl_add_u64 v[98:99], s[10:11], 0, v[96:97]
	s_lshl_b32 s18, s64, 5
	s_lshl_b32 s19, s64, 4
	s_mul_i32 s20, s64, 24
	s_mov_b32 s6, 0x3a800000
	v_mov_b32_e32 v96, 0x358637bd
	s_mov_b32 s21, 0x800000
	s_branch .LBB0_1475
	.p2align 6
